# residual epilogues start with 11/15 load quads instead of 9; EpiMla rope-load prefetch depth 8 -> 12
# speedup vs baseline: 1.0134x; 1.0020x over previous
; template <int K> __device__ __forceinline__ float swz(float v) { return __int_as_float(__builtin_amdgcn_ds_swizzle(__float_as_int(v), (K << 10) | 0x1f)); }
; __device__ __forceinline__ float x32_sum(float v) { auto r = __builtin_amdgcn_permlane32_swap(__float_as_uint(v), __float_as_uint(v), false, false); return __uint_as_float(r[0]) + __uint_as_float(r[1]); }
; __device__ __forceinline__ unsigned cvt_pk_bf16(float lo, float hi) { const f32x2c f = {lo, hi}; return __builtin_bit_cast(unsigned, __builtin_convertvector(f, bf16x2c)); }
;     __device__ __forceinline__ void operator()(const f32x4 (&acc)[2][2][4][2], const Unit& u, int wr, int wc, int, int) const {
;     ...
; #pragma unroll
;         for (int ai = 0; ai < 2; ++ai)
; #pragma unroll
;             for (int m = 0; m < 4; ++m) {
;                 const int row = rowb + ai * HALF + m * 16;
;                 float ss = 0.f;
; #pragma unroll
;                 for (int j = 0; j < 4; ++j) ss += acc[ai][0][m][0][j] * acc[ai][0][m][0][j] + acc[ai][0][m][1][j] * acc[ai][0][m][1][j] + acc[ai][1][m][0][j] * acc[ai][1][m][0][j] + acc[ai][1][m][1][j] * acc[ai][1][m][1][j];
;                 ss += ::swz<16>(ss); ss = ::x32_sum(ss);
;                 float rs = rsqrtf(ss * inv_cnt + 1e-6f) * sc; rs = is_v ? 1.0f : rs;
;                 const int pos = row & 2047, pp = rot ? ((fq & 1) ? (pos & 63) : (pos >> 6)) : 0;
;                 const float* rt = rope + pp * 16;
;                 bf16_t* dst = obase + (unsigned)(row * ostride + ocol);
; #pragma unroll
;                 for (int n = 0; n < 2; ++n) {
;                     const f32x4 g1 = *(const f32x4*)(g + 4 * n), g2 = *(const f32x4*)(g + sbj + 4 * n);
;                     const f32x4 t0 = *(const f32x4*)(rt + 8 * n), t1 = *(const f32x4*)(rt + 8 * n + 4);
;                     const f32x4 c = (f32x4){t0[0], t0[2], t1[0], t1[2]}, s = (f32x4){t0[1], t0[3], t1[1], t1[3]};
;                     const f32x4 a1 = acc[ai][0][m][n] * rs * g1, a2 = acc[ai][1][m][n] * rs * g2;
;                     const f32x4 o1 = a1 * c - a2 * s, o2 = a1 * s + a2 * c;
;                     if (st_ok) { u32x2 w; w.x = cvt_pk_bf16(o1[0], o1[1]); w.y = cvt_pk_bf16(o1[2], o1[3]); *(u32x2*)(dst + 4 * n) = w;
;                         w.x = cvt_pk_bf16(o2[0], o2[1]); w.y = cvt_pk_bf16(o2[2], o2[3]); *(u32x2*)(dst + sbj + 4 * n) = w; }
;                 }
.LBB0_669:
	v_and_b32_e32 v161, 15, v140
	v_mov_b32_e32 v140, 0x3c800000
	v_mov_b32_e32 v143, 0x3d000000
	v_lshlrev_b32_e32 v138, 2, v138
	v_mov_b32_e32 v139, v0
	v_cndmask_b32_e64 v159, v140, v143, s[42:43]
	v_mov_b32_e32 v140, 0x3e16c740
	v_lshl_add_u64 v[138:139], s[2:3], 0, v[138:139]
	global_load_dwordx4 v[172:175], v[138:139], off
	s_and_b64 s[2:3], s[40:41], exec
	v_cndmask_b32_e64 v143, 1.0, v140, s[40:41]
	v_cmp_gt_u32_e64 s[40:41], 2, v141
	v_mul_f32_e32 v140, v118, v118
	v_mul_f32_e32 v141, v119, v119
	v_fmac_f32_e32 v140, v126, v126
	v_fmac_f32_e32 v141, v127, v127
	v_fmac_f32_e32 v140, v122, v122
	v_fmac_f32_e32 v141, v123, v123
	v_fmac_f32_e32 v140, v114, v114
	v_fmac_f32_e32 v141, v115, v115
	v_add_f32_e32 v140, v140, v141
	v_mul_f32_e32 v141, v120, v120
	v_fmac_f32_e32 v141, v128, v128
	s_cselect_b32 s3, 0x16b98000, s76
	v_fmac_f32_e32 v141, v124, v124
	s_cselect_b32 s2, 0, 0
	s_add_u32 s60, s56, s3
	v_fmac_f32_e32 v141, v116, v116
	s_addc_u32 s61, s57, s2
	v_add_f32_e32 v140, v141, v140
	v_mul_f32_e32 v141, v121, v121
	s_cmpk_lt_i32 s54, 0x80
	v_fmac_f32_e32 v141, v129, v129
	s_cselect_b64 s[2:3], -1, 0
	v_fmac_f32_e32 v141, v125, v125
	s_and_b64 vcc, s[42:43], s[2:3]
	s_xor_b64 s[2:3], s[42:43], -1
	v_fmac_f32_e32 v141, v117, v117
	s_or_b64 s[20:21], s[2:3], s[40:41]
	v_cmp_eq_u32_e64 s[40:41], 0, v144
	v_add_f32_e32 v144, v141, v140
	ds_swizzle_b32 v145, v144 offset:swizzle(SWAP,16)
	s_lshl_b32 s2, s54, 8
	s_add_i32 s5, s2, s78
	s_and_b64 s[2:3], s[42:43], exec
	s_cselect_b32 s16, 8, 32
	s_waitcnt lgkmcnt(0)
	v_add_f32_e32 v158, v144, v145
	s_lshl_b32 s54, s16, 2
	v_mov_b32_e32 v162, v158
	v_or_b32_e32 v160, s5, v161
	v_lshl_add_u64 v[140:141], v[138:139], 0, s[54:55]
	s_bfe_u32 s17, s5, 0x50006
	v_mov_b32_e32 v248, s17
	v_cndmask_b32_e64 v248, v161, v248, s[40:41]
	v_lshlrev_b32_e32 v248, 4, v248
	v_cndmask_b32_e32 v248, 0, v248, vcc
	v_lshlrev_b32_e32 v249, 2, v248
	global_load_dwordx4 v[176:179], v249, s[22:23]
	global_load_dwordx4 v[180:183], v249, s[22:23] offset:16
	global_load_dwordx4 v[184:187], v[140:141], off
	global_load_dwordx4 v[188:191], v[138:139], off offset:16
	global_load_dwordx4 v[192:195], v249, s[22:23] offset:32
	global_load_dwordx4 v[196:199], v249, s[22:23] offset:48
	global_load_dwordx4 v[200:203], v[140:141], off offset:16
	global_load_dwordx4 v[204:207], v[138:139], off
	v_permlane32_swap_b32_e32 v158, v162
	s_and_saveexec_b64 s[2:3], s[20:21]
	v_add_f32_e32 v146, v158, v162
	v_mad_u64_u32 v[144:145], s[42:43], s26, v160, v[142:143]
	v_fmaak_f32 v146, v159, v146, 0x358637bd
	v_cmp_gt_f32_e64 s[42:43], s88, v146
	v_mul_f32_e32 v147, 0x4b800000, v146
	v_mov_b32_e32 v145, v0
	v_cndmask_b32_e64 v146, v146, v147, s[42:43]
	v_rsq_f32_e32 v146, v146
	v_lshl_add_u64 v[156:157], v[144:145], 1, s[60:61]
	s_lshl_b32 s54, s16, 1
	v_lshl_add_u64 v[144:145], v[156:157], 0, s[54:55]
	v_mul_f32_e32 v147, 0x45800000, v146
	v_cndmask_b32_e64 v146, v146, v147, s[42:43]
	v_mul_f32_e32 v146, v143, v146
	v_cndmask_b32_e64 v158, v146, 1.0, s[50:51]
	v_pk_mul_f32 v[146:147], v[128:129], v[158:159] op_sel_hi:[1,0]
	v_pk_mul_f32 v[148:149], v[126:127], v[158:159] op_sel_hi:[1,0]
	v_pk_mul_f32 v[150:151], v[122:123], v[158:159] op_sel_hi:[1,0]
	v_pk_mul_f32 v[152:153], v[124:125], v[158:159] op_sel_hi:[1,0]
	s_waitcnt vmcnt(8)
	v_pk_mul_f32 v[148:149], v[148:149], v[172:173]
	v_pk_mul_f32 v[146:147], v[146:147], v[174:175]
	v_or_b32_e32 v251, 16, v161
	v_mov_b32_e32 v223, s17
	v_cndmask_b32_e64 v223, v251, v223, s[40:41]
	v_lshlrev_b32_e32 v223, 4, v223
	v_cndmask_b32_e32 v223, 0, v223, vcc
	v_lshlrev_b32_e32 v216, 2, v223
	global_load_dwordx4 v[172:175], v216, s[22:23]
	global_load_dwordx4 v[212:215], v216, s[22:23] offset:16
	global_load_dwordx4 v[224:227], v[140:141], off
	global_load_dwordx4 v[228:231], v[138:139], off offset:16
	global_load_dwordx4 v[232:235], v216, s[22:23] offset:32
	global_load_dwordx4 v[236:239], v216, s[22:23] offset:48
	global_load_dwordx4 v[218:221], v[140:141], off offset:16
	s_waitcnt vmcnt(13)
	v_mov_b32_e32 v166, v180
	s_waitcnt vmcnt(12)
	v_pk_mul_f32 v[124:125], v[152:153], v[186:187]
	v_pk_mul_f32 v[122:123], v[150:151], v[184:185]
	v_mov_b32_e32 v150, v176
	v_mov_b32_e32 v151, v178
	v_mov_b32_e32 v167, v182
	v_mov_b32_e32 v182, v181
	v_mov_b32_e32 v178, v177
	v_pk_mul_f32 v[152:153], v[150:151], v[122:123]
	v_pk_mul_f32 v[168:169], v[166:167], v[124:125]
	v_pk_mul_f32 v[122:123], v[178:179], v[122:123]
	v_pk_mul_f32 v[124:125], v[182:183], v[124:125]
	v_pk_fma_f32 v[122:123], v[148:149], v[150:151], v[122:123] neg_lo:[0,0,1] neg_hi:[0,0,1]
	v_pk_fma_f32 v[124:125], v[146:147], v[166:167], v[124:125] neg_lo:[0,0,1] neg_hi:[0,0,1]
	v_pk_fma_f32 v[162:163], v[146:147], v[182:183], v[168:169]
	v_pk_fma_f32 v[126:127], v[148:149], v[178:179], v[152:153]
	v_cvt_pk_bf16_f32 v240, v122, v123
	v_cvt_pk_bf16_f32 v241, v124, v125
	v_cvt_pk_bf16_f32 v244, v126, v127
	v_cvt_pk_bf16_f32 v245, v162, v163
	v_pk_mul_f32 v[122:123], v[120:121], v[158:159] op_sel_hi:[1,0]
	v_pk_mul_f32 v[124:125], v[118:119], v[158:159] op_sel_hi:[1,0]
	global_load_dwordx4 v[176:179], v[138:139], off
	v_pk_mul_f32 v[146:147], v[114:115], v[158:159] op_sel_hi:[1,0]
	v_pk_mul_f32 v[148:149], v[116:117], v[158:159] op_sel_hi:[1,0]
	s_waitcnt vmcnt(12)
	v_pk_mul_f32 v[126:127], v[124:125], v[188:189]
	v_pk_mul_f32 v[128:129], v[122:123], v[190:191]
	s_waitcnt vmcnt(10)
	v_mov_b32_e32 v150, v196
	s_waitcnt vmcnt(9)
	v_pk_mul_f32 v[116:117], v[148:149], v[202:203]
	v_pk_mul_f32 v[114:115], v[146:147], v[200:201]
	v_mov_b32_e32 v146, v192
	v_mov_b32_e32 v147, v194
	v_mov_b32_e32 v151, v198
	v_mov_b32_e32 v198, v197
	v_mov_b32_e32 v194, v193
	v_pk_mul_f32 v[148:149], v[146:147], v[114:115]
	v_pk_mul_f32 v[152:153], v[150:151], v[116:117]
	v_pk_mul_f32 v[114:115], v[194:195], v[114:115]
	v_pk_mul_f32 v[116:117], v[198:199], v[116:117]
	v_pk_fma_f32 v[114:115], v[126:127], v[146:147], v[114:115] neg_lo:[0,0,1] neg_hi:[0,0,1]
	v_pk_fma_f32 v[116:117], v[128:129], v[150:151], v[116:117] neg_lo:[0,0,1] neg_hi:[0,0,1]
	v_pk_fma_f32 v[122:123], v[128:129], v[198:199], v[152:153]
	v_pk_fma_f32 v[118:119], v[126:127], v[194:195], v[148:149]
	v_cvt_pk_bf16_f32 v242, v114, v115
	v_cvt_pk_bf16_f32 v243, v116, v117
	global_store_dwordx4 v[156:157], v[240:243], off
	v_cvt_pk_bf16_f32 v246, v118, v119
	v_cvt_pk_bf16_f32 v247, v122, v123
	global_store_dwordx4 v[144:145], v[244:247], off
; template <int K> __device__ __forceinline__ float swz(float v) { return __int_as_float(__builtin_amdgcn_ds_swizzle(__float_as_int(v), (K << 10) | 0x1f)); }
; __device__ __forceinline__ float x32_sum(float v) { auto r = __builtin_amdgcn_permlane32_swap(__float_as_uint(v), __float_as_uint(v), false, false); return __uint_as_float(r[0]) + __uint_as_float(r[1]); }
;     __device__ __forceinline__ void operator()(const f32x4 (&acc)[2][2][4][2], const Unit& u, int wr, int wc, int, int) const {
;     ...
; #pragma unroll
;         for (int ai = 0; ai < 2; ++ai)
; #pragma unroll
;             for (int m = 0; m < 4; ++m) {
;                 const int row = rowb + ai * HALF + m * 16;
;                 float ss = 0.f;
; #pragma unroll
;                 for (int j = 0; j < 4; ++j) ss += acc[ai][0][m][0][j] * acc[ai][0][m][0][j] + acc[ai][0][m][1][j] * acc[ai][0][m][1][j] + acc[ai][1][m][0][j] * acc[ai][1][m][0][j] + acc[ai][1][m][1][j] * acc[ai][1][m][1][j];
;                 ss += ::swz<16>(ss); ss = ::x32_sum(ss);
;                 float rs = rsqrtf(ss * inv_cnt + 1e-6f) * sc; rs = is_v ? 1.0f : rs;
;                 const int pos = row & 2047, pp = rot ? ((fq & 1) ? (pos & 63) : (pos >> 6)) : 0;
;                 const float* rt = rope + pp * 16;
;                 bf16_t* dst = obase + (unsigned)(row * ostride + ocol);
; #pragma unroll
;                 for (int n = 0; n < 2; ++n) {
;                     const f32x4 g1 = *(const f32x4*)(g + 4 * n), g2 = *(const f32x4*)(g + sbj + 4 * n);
;                     const f32x4 t0 = *(const f32x4*)(rt + 8 * n), t1 = *(const f32x4*)(rt + 8 * n + 4);
;                     const f32x4 c = (f32x4){t0[0], t0[2], t1[0], t1[2]}, s = (f32x4){t0[1], t0[3], t1[1], t1[3]};
;                     const f32x4 a1 = acc[ai][0][m][n] * rs * g1, a2 = acc[ai][1][m][n] * rs * g2;
;                     const f32x4 o1 = a1 * c - a2 * s, o2 = a1 * s + a2 * c;
;                     if (st_ok) { u32x2 w; w.x = cvt_pk_bf16(o1[0], o1[1]); w.y = cvt_pk_bf16(o1[2], o1[3]); *(u32x2*)(dst + 4 * n) = w;
;                         w.x = cvt_pk_bf16(o2[0], o2[1]); w.y = cvt_pk_bf16(o2[2], o2[3]); *(u32x2*)(dst + sbj + 4 * n) = w; }
;                 }
;                 asm volatile("" ::: "memory");
;             }
.LBB0_671:
	s_or_b64 exec, exec, s[2:3]
	v_mul_f32_e32 v114, v102, v102
	v_mul_f32_e32 v115, v103, v103
	v_fmac_f32_e32 v114, v110, v110
	v_fmac_f32_e32 v115, v111, v111
	v_fmac_f32_e32 v114, v106, v106
	v_fmac_f32_e32 v115, v107, v107
	v_fmac_f32_e32 v114, v98, v98
	v_fmac_f32_e32 v115, v99, v99
	v_add_f32_e32 v114, v114, v115
	v_mul_f32_e32 v115, v104, v104
	v_fmac_f32_e32 v115, v112, v112
	v_fmac_f32_e32 v115, v108, v108
	v_fmac_f32_e32 v115, v100, v100
	v_add_f32_e32 v114, v115, v114
	v_mul_f32_e32 v115, v105, v105
	v_fmac_f32_e32 v115, v113, v113
	v_fmac_f32_e32 v115, v109, v109
	v_fmac_f32_e32 v115, v101, v101
	v_add_f32_e32 v114, v115, v114
	ds_swizzle_b32 v115, v114 offset:swizzle(SWAP,16)
	v_or_b32_e32 v119, 16, v161
	s_waitcnt lgkmcnt(0)
	v_add_f32_e32 v118, v114, v115
	v_mov_b32_e32 v120, v118
	s_nop 1
	v_permlane32_swap_b32_e32 v118, v120
	s_and_saveexec_b64 s[2:3], s[20:21]
	v_or_b32_e32 v114, 16, v160
	v_add_f32_e32 v118, v118, v120
	v_mad_u64_u32 v[114:115], s[42:43], s26, v114, v[142:143]
	v_fmaak_f32 v118, v159, v118, 0x358637bd
	v_cmp_gt_f32_e64 s[42:43], s88, v118
	v_mul_f32_e32 v120, 0x4b800000, v118
	v_mov_b32_e32 v115, v0
	v_cndmask_b32_e64 v118, v118, v120, s[42:43]
	v_rsq_f32_e32 v118, v118
	v_lshl_add_u64 v[116:117], v[114:115], 1, s[60:61]
	s_lshl_b32 s54, s16, 1
	v_lshl_add_u64 v[114:115], v[116:117], 0, s[54:55]
	v_mul_f32_e32 v120, 0x45800000, v118
	v_cndmask_b32_e64 v118, v118, v120, s[42:43]
	v_mul_f32_e32 v118, v143, v118
	v_cndmask_b32_e64 v118, v118, 1.0, s[50:51]
	v_pk_mul_f32 v[120:121], v[112:113], v[118:119] op_sel_hi:[1,0]
	v_pk_mul_f32 v[122:123], v[110:111], v[118:119] op_sel_hi:[1,0]
	v_pk_mul_f32 v[128:129], v[106:107], v[118:119] op_sel_hi:[1,0]
	v_pk_mul_f32 v[144:145], v[108:109], v[118:119] op_sel_hi:[1,0]
	s_waitcnt vmcnt(10)
	v_pk_mul_f32 v[124:125], v[122:123], v[204:205]
	v_pk_mul_f32 v[126:127], v[120:121], v[206:207]
	v_or_b32_e32 v248, 32, v161
	v_mov_b32_e32 v250, s17
	v_cndmask_b32_e64 v250, v248, v250, s[40:41]
	v_lshlrev_b32_e32 v250, 4, v250
	v_cndmask_b32_e32 v250, 0, v250, vcc
	v_lshlrev_b32_e32 v249, 2, v250
	global_load_dwordx4 v[180:183], v249, s[22:23]
	global_load_dwordx4 v[184:187], v249, s[22:23] offset:16
	global_load_dwordx4 v[188:191], v[140:141], off
	global_load_dwordx4 v[192:195], v[138:139], off offset:16
	global_load_dwordx4 v[196:199], v249, s[22:23] offset:32
	global_load_dwordx4 v[200:203], v249, s[22:23] offset:48
	global_load_dwordx4 v[204:207], v[140:141], off offset:16
	s_waitcnt vmcnt(15)
	v_mov_b32_e32 v146, v212
	s_waitcnt vmcnt(14)
	v_pk_mul_f32 v[108:109], v[144:145], v[226:227]
	v_pk_mul_f32 v[106:107], v[128:129], v[224:225]
	v_mov_b32_e32 v128, v172
	v_mov_b32_e32 v129, v174
	v_mov_b32_e32 v147, v214
	v_mov_b32_e32 v214, v213
	v_mov_b32_e32 v174, v173
	v_pk_mul_f32 v[144:145], v[128:129], v[106:107]
	v_pk_mul_f32 v[148:149], v[146:147], v[108:109]
	v_pk_mul_f32 v[106:107], v[174:175], v[106:107]
	v_pk_mul_f32 v[108:109], v[214:215], v[108:109]
	v_pk_fma_f32 v[106:107], v[124:125], v[128:129], v[106:107] neg_lo:[0,0,1] neg_hi:[0,0,1]
	v_pk_fma_f32 v[108:109], v[126:127], v[146:147], v[108:109] neg_lo:[0,0,1] neg_hi:[0,0,1]
	v_pk_fma_f32 v[120:121], v[126:127], v[214:215], v[148:149]
	v_pk_fma_f32 v[110:111], v[124:125], v[174:175], v[144:145]
	v_cvt_pk_bf16_f32 v240, v106, v107
	v_cvt_pk_bf16_f32 v241, v108, v109
	v_cvt_pk_bf16_f32 v244, v110, v111
	v_cvt_pk_bf16_f32 v245, v120, v121
	v_pk_mul_f32 v[106:107], v[104:105], v[118:119] op_sel_hi:[1,0]
	v_pk_mul_f32 v[108:109], v[102:103], v[118:119] op_sel_hi:[1,0]
	global_load_dwordx4 v[172:175], v[138:139], off
	v_pk_mul_f32 v[120:121], v[98:99], v[118:119] op_sel_hi:[1,0]
	v_pk_mul_f32 v[122:123], v[100:101], v[118:119] op_sel_hi:[1,0]
	s_waitcnt vmcnt(14)
	v_pk_mul_f32 v[110:111], v[108:109], v[228:229]
	v_pk_mul_f32 v[112:113], v[106:107], v[230:231]
	s_waitcnt vmcnt(12)
	v_mov_b32_e32 v124, v236
	s_waitcnt vmcnt(11)
	v_pk_mul_f32 v[100:101], v[122:123], v[220:221]
	v_pk_mul_f32 v[98:99], v[120:121], v[218:219]
	v_mov_b32_e32 v120, v232
	v_mov_b32_e32 v121, v234
	v_mov_b32_e32 v125, v238
	v_mov_b32_e32 v238, v237
	v_mov_b32_e32 v234, v233
	v_pk_mul_f32 v[122:123], v[120:121], v[98:99]
	v_pk_mul_f32 v[126:127], v[124:125], v[100:101]
	v_pk_mul_f32 v[98:99], v[234:235], v[98:99]
	v_pk_mul_f32 v[100:101], v[238:239], v[100:101]
	v_pk_fma_f32 v[98:99], v[110:111], v[120:121], v[98:99] neg_lo:[0,0,1] neg_hi:[0,0,1]
	v_pk_fma_f32 v[100:101], v[112:113], v[124:125], v[100:101] neg_lo:[0,0,1] neg_hi:[0,0,1]
	v_pk_fma_f32 v[106:107], v[112:113], v[238:239], v[126:127]
	v_pk_fma_f32 v[102:103], v[110:111], v[234:235], v[122:123]
	v_cvt_pk_bf16_f32 v242, v98, v99
	v_cvt_pk_bf16_f32 v243, v100, v101
	global_store_dwordx4 v[116:117], v[240:243], off
	v_cvt_pk_bf16_f32 v246, v102, v103
	v_cvt_pk_bf16_f32 v247, v106, v107
	global_store_dwordx4 v[114:115], v[244:247], off
; template <int K> __device__ __forceinline__ float swz(float v) { return __int_as_float(__builtin_amdgcn_ds_swizzle(__float_as_int(v), (K << 10) | 0x1f)); }
; __device__ __forceinline__ float x32_sum(float v) { auto r = __builtin_amdgcn_permlane32_swap(__float_as_uint(v), __float_as_uint(v), false, false); return __uint_as_float(r[0]) + __uint_as_float(r[1]); }
;     __device__ __forceinline__ void operator()(const f32x4 (&acc)[2][2][4][2], const Unit& u, int wr, int wc, int, int) const {
;     ...
; #pragma unroll
;         for (int ai = 0; ai < 2; ++ai)
; #pragma unroll
;             for (int m = 0; m < 4; ++m) {
;                 const int row = rowb + ai * HALF + m * 16;
;                 float ss = 0.f;
; #pragma unroll
;                 for (int j = 0; j < 4; ++j) ss += acc[ai][0][m][0][j] * acc[ai][0][m][0][j] + acc[ai][0][m][1][j] * acc[ai][0][m][1][j] + acc[ai][1][m][0][j] * acc[ai][1][m][0][j] + acc[ai][1][m][1][j] * acc[ai][1][m][1][j];
;                 ss += ::swz<16>(ss); ss = ::x32_sum(ss);
;                 float rs = rsqrtf(ss * inv_cnt + 1e-6f) * sc; rs = is_v ? 1.0f : rs;
;                 const int pos = row & 2047, pp = rot ? ((fq & 1) ? (pos & 63) : (pos >> 6)) : 0;
;                 const float* rt = rope + pp * 16;
;                 bf16_t* dst = obase + (unsigned)(row * ostride + ocol);
; #pragma unroll
;                 for (int n = 0; n < 2; ++n) {
;                     const f32x4 g1 = *(const f32x4*)(g + 4 * n), g2 = *(const f32x4*)(g + sbj + 4 * n);
;                     const f32x4 t0 = *(const f32x4*)(rt + 8 * n), t1 = *(const f32x4*)(rt + 8 * n + 4);
;                     const f32x4 c = (f32x4){t0[0], t0[2], t1[0], t1[2]}, s = (f32x4){t0[1], t0[3], t1[1], t1[3]};
;                     const f32x4 a1 = acc[ai][0][m][n] * rs * g1, a2 = acc[ai][1][m][n] * rs * g2;
;                     const f32x4 o1 = a1 * c - a2 * s, o2 = a1 * s + a2 * c;
;                     if (st_ok) { u32x2 w; w.x = cvt_pk_bf16(o1[0], o1[1]); w.y = cvt_pk_bf16(o1[2], o1[3]); *(u32x2*)(dst + 4 * n) = w;
;                         w.x = cvt_pk_bf16(o2[0], o2[1]); w.y = cvt_pk_bf16(o2[2], o2[3]); *(u32x2*)(dst + sbj + 4 * n) = w; }
;                 }
;                 asm volatile("" ::: "memory");
;             }
.LBB0_673:
	s_or_b64 exec, exec, s[2:3]
	v_mul_f32_e32 v98, v86, v86
	v_mul_f32_e32 v99, v87, v87
	v_fmac_f32_e32 v98, v94, v94
	v_fmac_f32_e32 v99, v95, v95
	v_fmac_f32_e32 v98, v90, v90
	v_fmac_f32_e32 v99, v91, v91
	v_fmac_f32_e32 v98, v82, v82
	v_fmac_f32_e32 v99, v83, v83
	v_add_f32_e32 v98, v98, v99
	v_mul_f32_e32 v99, v88, v88
	v_fmac_f32_e32 v99, v96, v96
	v_fmac_f32_e32 v99, v92, v92
	v_fmac_f32_e32 v99, v84, v84
	v_add_f32_e32 v98, v99, v98
	v_mul_f32_e32 v99, v89, v89
	v_fmac_f32_e32 v99, v97, v97
	v_fmac_f32_e32 v99, v93, v93
	v_fmac_f32_e32 v99, v85, v85
	v_add_f32_e32 v98, v99, v98
	ds_swizzle_b32 v99, v98 offset:swizzle(SWAP,16)
	v_or_b32_e32 v103, 32, v161
	s_waitcnt lgkmcnt(0)
	v_add_f32_e32 v102, v98, v99
	v_mov_b32_e32 v104, v102
	s_nop 1
	v_permlane32_swap_b32_e32 v102, v104
	s_and_saveexec_b64 s[2:3], s[20:21]
	v_or_b32_e32 v98, 32, v160
	v_add_f32_e32 v102, v102, v104
	v_mad_u64_u32 v[98:99], s[42:43], s26, v98, v[142:143]
	v_fmaak_f32 v102, v159, v102, 0x358637bd
	v_cmp_gt_f32_e64 s[42:43], s88, v102
	v_mul_f32_e32 v104, 0x4b800000, v102
	v_mov_b32_e32 v99, v0
	v_cndmask_b32_e64 v102, v102, v104, s[42:43]
	v_rsq_f32_e32 v102, v102
	v_lshl_add_u64 v[100:101], v[98:99], 1, s[60:61]
	s_lshl_b32 s54, s16, 1
	v_lshl_add_u64 v[98:99], v[100:101], 0, s[54:55]
	v_mul_f32_e32 v104, 0x45800000, v102
	v_cndmask_b32_e64 v102, v102, v104, s[42:43]
	v_mul_f32_e32 v102, v143, v102
	v_cndmask_b32_e64 v102, v102, 1.0, s[50:51]
	v_pk_mul_f32 v[104:105], v[96:97], v[102:103] op_sel_hi:[1,0]
	v_pk_mul_f32 v[106:107], v[94:95], v[102:103] op_sel_hi:[1,0]
	v_pk_mul_f32 v[112:113], v[90:91], v[102:103] op_sel_hi:[1,0]
	v_pk_mul_f32 v[114:115], v[92:93], v[102:103] op_sel_hi:[1,0]
	s_waitcnt vmcnt(12)
	v_pk_mul_f32 v[108:109], v[106:107], v[176:177]
	v_pk_mul_f32 v[110:111], v[104:105], v[178:179]
	v_or_b32_e32 v251, 48, v161
	v_mov_b32_e32 v223, s17
	v_cndmask_b32_e64 v223, v251, v223, s[40:41]
	v_lshlrev_b32_e32 v223, 4, v223
	v_cndmask_b32_e32 v223, 0, v223, vcc
	v_lshlrev_b32_e32 v216, 2, v223
	global_load_dwordx4 v[176:179], v216, s[22:23]
	global_load_dwordx4 v[212:215], v216, s[22:23] offset:16
	global_load_dwordx4 v[224:227], v[140:141], off
	global_load_dwordx4 v[228:231], v[138:139], off offset:16
	global_load_dwordx4 v[232:235], v216, s[22:23] offset:32
	global_load_dwordx4 v[236:239], v216, s[22:23] offset:48
	global_load_dwordx4 v[218:221], v[140:141], off offset:16
	s_waitcnt vmcnt(15)
	v_mov_b32_e32 v116, v184
	s_waitcnt vmcnt(14)
	v_pk_mul_f32 v[92:93], v[114:115], v[190:191]
	v_pk_mul_f32 v[90:91], v[112:113], v[188:189]
	v_mov_b32_e32 v112, v180
	v_mov_b32_e32 v113, v182
	v_mov_b32_e32 v117, v186
	v_mov_b32_e32 v186, v185
	v_mov_b32_e32 v182, v181
	v_pk_mul_f32 v[114:115], v[112:113], v[90:91]
	v_pk_mul_f32 v[120:121], v[116:117], v[92:93]
	v_pk_mul_f32 v[90:91], v[182:183], v[90:91]
	v_pk_mul_f32 v[92:93], v[186:187], v[92:93]
	v_pk_fma_f32 v[90:91], v[108:109], v[112:113], v[90:91] neg_lo:[0,0,1] neg_hi:[0,0,1]
	v_pk_fma_f32 v[92:93], v[110:111], v[116:117], v[92:93] neg_lo:[0,0,1] neg_hi:[0,0,1]
	v_pk_fma_f32 v[104:105], v[110:111], v[186:187], v[120:121]
	v_pk_fma_f32 v[94:95], v[108:109], v[182:183], v[114:115]
	v_cvt_pk_bf16_f32 v240, v90, v91
	v_cvt_pk_bf16_f32 v241, v92, v93
	v_cvt_pk_bf16_f32 v244, v94, v95
	v_cvt_pk_bf16_f32 v245, v104, v105
	v_pk_mul_f32 v[90:91], v[88:89], v[102:103] op_sel_hi:[1,0]
	v_pk_mul_f32 v[92:93], v[86:87], v[102:103] op_sel_hi:[1,0]
	global_load_dwordx4 v[180:183], v[138:139], off
	v_pk_mul_f32 v[104:105], v[82:83], v[102:103] op_sel_hi:[1,0]
	v_pk_mul_f32 v[106:107], v[84:85], v[102:103] op_sel_hi:[1,0]
	s_waitcnt vmcnt(14)
	v_pk_mul_f32 v[94:95], v[92:93], v[192:193]
	v_pk_mul_f32 v[96:97], v[90:91], v[194:195]
	s_waitcnt vmcnt(12)
	v_mov_b32_e32 v108, v200
	s_waitcnt vmcnt(11)
	v_pk_mul_f32 v[84:85], v[106:107], v[206:207]
	v_pk_mul_f32 v[82:83], v[104:105], v[204:205]
	v_mov_b32_e32 v104, v196
	v_mov_b32_e32 v105, v198
	v_mov_b32_e32 v109, v202
	v_mov_b32_e32 v202, v201
	v_mov_b32_e32 v198, v197
	v_pk_mul_f32 v[106:107], v[104:105], v[82:83]
	v_pk_mul_f32 v[110:111], v[108:109], v[84:85]
	v_pk_mul_f32 v[82:83], v[198:199], v[82:83]
	v_pk_mul_f32 v[84:85], v[202:203], v[84:85]
	v_pk_fma_f32 v[82:83], v[94:95], v[104:105], v[82:83] neg_lo:[0,0,1] neg_hi:[0,0,1]
	v_pk_fma_f32 v[84:85], v[96:97], v[108:109], v[84:85] neg_lo:[0,0,1] neg_hi:[0,0,1]
	v_pk_fma_f32 v[90:91], v[96:97], v[202:203], v[110:111]
	v_pk_fma_f32 v[86:87], v[94:95], v[198:199], v[106:107]
	v_cvt_pk_bf16_f32 v242, v82, v83
	v_cvt_pk_bf16_f32 v243, v84, v85
	global_store_dwordx4 v[100:101], v[240:243], off
	v_cvt_pk_bf16_f32 v246, v86, v87
	v_cvt_pk_bf16_f32 v247, v90, v91
	global_store_dwordx4 v[98:99], v[244:247], off
; template <int K> __device__ __forceinline__ float swz(float v) { return __int_as_float(__builtin_amdgcn_ds_swizzle(__float_as_int(v), (K << 10) | 0x1f)); }
; __device__ __forceinline__ float x32_sum(float v) { auto r = __builtin_amdgcn_permlane32_swap(__float_as_uint(v), __float_as_uint(v), false, false); return __uint_as_float(r[0]) + __uint_as_float(r[1]); }
;     __device__ __forceinline__ void operator()(const f32x4 (&acc)[2][2][4][2], const Unit& u, int wr, int wc, int, int) const {
;     ...
; #pragma unroll
;         for (int ai = 0; ai < 2; ++ai)
; #pragma unroll
;             for (int m = 0; m < 4; ++m) {
;                 const int row = rowb + ai * HALF + m * 16;
;                 float ss = 0.f;
; #pragma unroll
;                 for (int j = 0; j < 4; ++j) ss += acc[ai][0][m][0][j] * acc[ai][0][m][0][j] + acc[ai][0][m][1][j] * acc[ai][0][m][1][j] + acc[ai][1][m][0][j] * acc[ai][1][m][0][j] + acc[ai][1][m][1][j] * acc[ai][1][m][1][j];
;                 ss += ::swz<16>(ss); ss = ::x32_sum(ss);
;                 float rs = rsqrtf(ss * inv_cnt + 1e-6f) * sc; rs = is_v ? 1.0f : rs;
;                 const int pos = row & 2047, pp = rot ? ((fq & 1) ? (pos & 63) : (pos >> 6)) : 0;
;                 const float* rt = rope + pp * 16;
;                 bf16_t* dst = obase + (unsigned)(row * ostride + ocol);
; #pragma unroll
;                 for (int n = 0; n < 2; ++n) {
;                     const f32x4 g1 = *(const f32x4*)(g + 4 * n), g2 = *(const f32x4*)(g + sbj + 4 * n);
;                     const f32x4 t0 = *(const f32x4*)(rt + 8 * n), t1 = *(const f32x4*)(rt + 8 * n + 4);
;                     const f32x4 c = (f32x4){t0[0], t0[2], t1[0], t1[2]}, s = (f32x4){t0[1], t0[3], t1[1], t1[3]};
;                     const f32x4 a1 = acc[ai][0][m][n] * rs * g1, a2 = acc[ai][1][m][n] * rs * g2;
;                     const f32x4 o1 = a1 * c - a2 * s, o2 = a1 * s + a2 * c;
;                     if (st_ok) { u32x2 w; w.x = cvt_pk_bf16(o1[0], o1[1]); w.y = cvt_pk_bf16(o1[2], o1[3]); *(u32x2*)(dst + 4 * n) = w;
;                         w.x = cvt_pk_bf16(o2[0], o2[1]); w.y = cvt_pk_bf16(o2[2], o2[3]); *(u32x2*)(dst + sbj + 4 * n) = w; }
;                 }
;                 asm volatile("" ::: "memory");
;             }
.LBB0_675:
	s_or_b64 exec, exec, s[2:3]
	v_mul_f32_e32 v82, v70, v70
	v_mul_f32_e32 v83, v71, v71
	v_fmac_f32_e32 v82, v78, v78
	v_fmac_f32_e32 v83, v79, v79
	v_fmac_f32_e32 v82, v74, v74
	v_fmac_f32_e32 v83, v75, v75
	v_fmac_f32_e32 v82, v66, v66
	v_fmac_f32_e32 v83, v67, v67
	v_add_f32_e32 v82, v82, v83
	v_mul_f32_e32 v83, v72, v72
	v_fmac_f32_e32 v83, v80, v80
	v_fmac_f32_e32 v83, v76, v76
	v_fmac_f32_e32 v83, v68, v68
	v_add_f32_e32 v82, v83, v82
	v_mul_f32_e32 v83, v73, v73
	v_fmac_f32_e32 v83, v81, v81
	v_fmac_f32_e32 v83, v77, v77
	v_fmac_f32_e32 v83, v69, v69
	v_add_f32_e32 v82, v83, v82
	ds_swizzle_b32 v83, v82 offset:swizzle(SWAP,16)
	v_or_b32_e32 v87, 48, v161
	s_waitcnt lgkmcnt(0)
	v_add_f32_e32 v86, v82, v83
	v_mov_b32_e32 v88, v86
	s_nop 1
	v_permlane32_swap_b32_e32 v86, v88
	s_and_saveexec_b64 s[2:3], s[20:21]
	v_or_b32_e32 v82, 48, v160
	v_add_f32_e32 v86, v86, v88
	v_mad_u64_u32 v[82:83], s[42:43], s26, v82, v[142:143]
	v_fmaak_f32 v86, v159, v86, 0x358637bd
	v_cmp_gt_f32_e64 s[42:43], s88, v86
	v_mul_f32_e32 v88, 0x4b800000, v86
	v_mov_b32_e32 v83, v0
	v_cndmask_b32_e64 v86, v86, v88, s[42:43]
	v_rsq_f32_e32 v86, v86
	v_lshl_add_u64 v[84:85], v[82:83], 1, s[60:61]
	s_lshl_b32 s54, s16, 1
	v_lshl_add_u64 v[82:83], v[84:85], 0, s[54:55]
	v_mul_f32_e32 v88, 0x45800000, v86
	v_cndmask_b32_e64 v86, v86, v88, s[42:43]
	v_mul_f32_e32 v86, v143, v86
	v_cndmask_b32_e64 v86, v86, 1.0, s[50:51]
	v_pk_mul_f32 v[88:89], v[80:81], v[86:87] op_sel_hi:[1,0]
	v_pk_mul_f32 v[90:91], v[78:79], v[86:87] op_sel_hi:[1,0]
	v_pk_mul_f32 v[96:97], v[74:75], v[86:87] op_sel_hi:[1,0]
	v_pk_mul_f32 v[98:99], v[76:77], v[86:87] op_sel_hi:[1,0]
	s_waitcnt vmcnt(12)
	v_pk_mul_f32 v[92:93], v[90:91], v[172:173]
	v_pk_mul_f32 v[94:95], v[88:89], v[174:175]
	s_waitcnt vmcnt(8)
	v_mov_b32_e32 v100, v212
	s_waitcnt vmcnt(7)
	v_pk_mul_f32 v[76:77], v[98:99], v[226:227]
	v_pk_mul_f32 v[74:75], v[96:97], v[224:225]
	v_mov_b32_e32 v96, v176
	v_mov_b32_e32 v97, v178
	v_mov_b32_e32 v101, v214
	v_mov_b32_e32 v214, v213
	v_mov_b32_e32 v178, v177
	v_pk_mul_f32 v[98:99], v[96:97], v[74:75]
	v_pk_mul_f32 v[104:105], v[100:101], v[76:77]
	v_pk_mul_f32 v[74:75], v[178:179], v[74:75]
	v_pk_mul_f32 v[76:77], v[214:215], v[76:77]
	v_pk_fma_f32 v[74:75], v[92:93], v[96:97], v[74:75] neg_lo:[0,0,1] neg_hi:[0,0,1]
	v_pk_fma_f32 v[76:77], v[94:95], v[100:101], v[76:77] neg_lo:[0,0,1] neg_hi:[0,0,1]
	v_pk_fma_f32 v[88:89], v[94:95], v[214:215], v[104:105]
	v_pk_fma_f32 v[78:79], v[92:93], v[178:179], v[98:99]
	v_cvt_pk_bf16_f32 v240, v74, v75
	v_cvt_pk_bf16_f32 v241, v76, v77
	v_cvt_pk_bf16_f32 v244, v78, v79
	v_cvt_pk_bf16_f32 v245, v88, v89
	v_pk_mul_f32 v[74:75], v[72:73], v[86:87] op_sel_hi:[1,0]
	v_pk_mul_f32 v[76:77], v[70:71], v[86:87] op_sel_hi:[1,0]
	v_pk_mul_f32 v[88:89], v[66:67], v[86:87] op_sel_hi:[1,0]
	v_pk_mul_f32 v[90:91], v[68:69], v[86:87] op_sel_hi:[1,0]
	s_waitcnt vmcnt(6)
	v_pk_mul_f32 v[78:79], v[76:77], v[228:229]
	v_pk_mul_f32 v[80:81], v[74:75], v[230:231]
	s_waitcnt vmcnt(4)
	v_mov_b32_e32 v92, v236
	s_waitcnt vmcnt(3)
	v_pk_mul_f32 v[68:69], v[90:91], v[220:221]
	v_pk_mul_f32 v[66:67], v[88:89], v[218:219]
	v_mov_b32_e32 v88, v232
	v_mov_b32_e32 v89, v234
	v_mov_b32_e32 v93, v238
	v_mov_b32_e32 v238, v237
	v_mov_b32_e32 v234, v233
	v_pk_mul_f32 v[90:91], v[88:89], v[66:67]
	v_pk_mul_f32 v[94:95], v[92:93], v[68:69]
	v_pk_mul_f32 v[66:67], v[234:235], v[66:67]
	v_pk_mul_f32 v[68:69], v[238:239], v[68:69]
	v_pk_fma_f32 v[66:67], v[78:79], v[88:89], v[66:67] neg_lo:[0,0,1] neg_hi:[0,0,1]
	v_pk_fma_f32 v[68:69], v[80:81], v[92:93], v[68:69] neg_lo:[0,0,1] neg_hi:[0,0,1]
	v_pk_fma_f32 v[74:75], v[80:81], v[238:239], v[94:95]
	v_pk_fma_f32 v[70:71], v[78:79], v[234:235], v[90:91]
	v_cvt_pk_bf16_f32 v242, v66, v67
	v_cvt_pk_bf16_f32 v243, v68, v69
	global_store_dwordx4 v[84:85], v[240:243], off
	v_cvt_pk_bf16_f32 v246, v70, v71
	v_cvt_pk_bf16_f32 v247, v74, v75
	global_store_dwordx4 v[82:83], v[244:247], off
.LBB0_677:
	s_or_b64 exec, exec, s[2:3]
	v_mul_f32_e32 v66, v54, v54
	v_mul_f32_e32 v67, v55, v55
	v_fmac_f32_e32 v66, v62, v62
	v_fmac_f32_e32 v67, v63, v63
	v_fmac_f32_e32 v66, v58, v58
	v_fmac_f32_e32 v67, v59, v59
	v_fmac_f32_e32 v66, v50, v50
	v_fmac_f32_e32 v67, v51, v51
	v_add_f32_e32 v66, v66, v67
	v_mul_f32_e32 v67, v56, v56
	v_fmac_f32_e32 v67, v64, v64
	v_fmac_f32_e32 v67, v60, v60
	v_fmac_f32_e32 v67, v52, v52
	v_add_f32_e32 v66, v67, v66
	v_mul_f32_e32 v67, v57, v57
	v_fmac_f32_e32 v67, v65, v65
	v_fmac_f32_e32 v67, v61, v61
	v_fmac_f32_e32 v67, v53, v53
	v_add_f32_e32 v67, v67, v66
	ds_swizzle_b32 v68, v67 offset:swizzle(SWAP,16)
	v_add_u32_e32 v66, 0x80, v160
	v_bfe_u32 v71, v66, 6, 5
	v_cndmask_b32_e64 v248, v161, v71, s[40:41]
	v_lshlrev_b32_e32 v248, 4, v248
	v_cndmask_b32_e32 v248, 0, v248, vcc
	v_lshlrev_b32_e32 v249, 2, v248
	global_load_dwordx4 v[172:175], v249, s[22:23]
	global_load_dwordx4 v[176:179], v249, s[22:23] offset:16
	global_load_dwordx4 v[184:187], v[140:141], off
	global_load_dwordx4 v[188:191], v[138:139], off offset:16
	global_load_dwordx4 v[192:195], v249, s[22:23] offset:32
	global_load_dwordx4 v[196:199], v249, s[22:23] offset:48
	global_load_dwordx4 v[200:203], v[140:141], off offset:16
	global_load_dwordx4 v[204:207], v[138:139], off
	s_waitcnt lgkmcnt(0)
; template <int K> __device__ __forceinline__ float swz(float v) { return __int_as_float(__builtin_amdgcn_ds_swizzle(__float_as_int(v), (K << 10) | 0x1f)); }
; __device__ __forceinline__ float x32_sum(float v) { auto r = __builtin_amdgcn_permlane32_swap(__float_as_uint(v), __float_as_uint(v), false, false); return __uint_as_float(r[0]) + __uint_as_float(r[1]); }
;     __device__ __forceinline__ void operator()(const f32x4 (&acc)[2][2][4][2], const Unit& u, int wr, int wc, int, int) const {
;     ...
; #pragma unroll
;         for (int ai = 0; ai < 2; ++ai)
; #pragma unroll
;             for (int m = 0; m < 4; ++m) {
;                 const int row = rowb + ai * HALF + m * 16;
;                 float ss = 0.f;
; #pragma unroll
;                 for (int j = 0; j < 4; ++j) ss += acc[ai][0][m][0][j] * acc[ai][0][m][0][j] + acc[ai][0][m][1][j] * acc[ai][0][m][1][j] + acc[ai][1][m][0][j] * acc[ai][1][m][0][j] + acc[ai][1][m][1][j] * acc[ai][1][m][1][j];
;                 ss += ::swz<16>(ss); ss = ::x32_sum(ss);
;                 float rs = rsqrtf(ss * inv_cnt + 1e-6f) * sc; rs = is_v ? 1.0f : rs;
;                 const int pos = row & 2047, pp = rot ? ((fq & 1) ? (pos & 63) : (pos >> 6)) : 0;
;                 const float* rt = rope + pp * 16;
;                 bf16_t* dst = obase + (unsigned)(row * ostride + ocol);
; #pragma unroll
;                 for (int n = 0; n < 2; ++n) {
;                     const f32x4 g1 = *(const f32x4*)(g + 4 * n), g2 = *(const f32x4*)(g + sbj + 4 * n);
;                     const f32x4 t0 = *(const f32x4*)(rt + 8 * n), t1 = *(const f32x4*)(rt + 8 * n + 4);
;                     const f32x4 c = (f32x4){t0[0], t0[2], t1[0], t1[2]}, s = (f32x4){t0[1], t0[3], t1[1], t1[3]};
;                     const f32x4 a1 = acc[ai][0][m][n] * rs * g1, a2 = acc[ai][1][m][n] * rs * g2;
;                     const f32x4 o1 = a1 * c - a2 * s, o2 = a1 * s + a2 * c;
;                     if (st_ok) { u32x2 w; w.x = cvt_pk_bf16(o1[0], o1[1]); w.y = cvt_pk_bf16(o1[2], o1[3]); *(u32x2*)(dst + 4 * n) = w;
;                         w.x = cvt_pk_bf16(o2[0], o2[1]); w.y = cvt_pk_bf16(o2[2], o2[3]); *(u32x2*)(dst + sbj + 4 * n) = w; }
;                 }
;                 asm volatile("" ::: "memory");
;             }
	v_add_f32_e32 v70, v67, v68
	v_mov_b32_e32 v72, v70
	s_nop 1
	v_permlane32_swap_b32_e32 v70, v72
	s_and_saveexec_b64 s[2:3], s[20:21]
	v_add_f32_e32 v70, v70, v72
	v_mad_u64_u32 v[66:67], s[42:43], s26, v66, v[142:143]
	v_fmaak_f32 v70, v159, v70, 0x358637bd
	v_cmp_gt_f32_e64 s[42:43], s88, v70
	v_mul_f32_e32 v72, 0x4b800000, v70
	v_mov_b32_e32 v67, v0
	v_cndmask_b32_e64 v70, v70, v72, s[42:43]
	v_rsq_f32_e32 v70, v70
	v_lshl_add_u64 v[68:69], v[66:67], 1, s[60:61]
	s_lshl_b32 s54, s16, 1
	v_lshl_add_u64 v[66:67], v[68:69], 0, s[54:55]
	v_mul_f32_e32 v72, 0x45800000, v70
	v_cndmask_b32_e64 v70, v70, v72, s[42:43]
	v_mul_f32_e32 v70, v143, v70
	v_cndmask_b32_e64 v70, v70, 1.0, s[50:51]
	v_pk_mul_f32 v[72:73], v[64:65], v[70:71] op_sel_hi:[1,0]
	v_pk_mul_f32 v[74:75], v[62:63], v[70:71] op_sel_hi:[1,0]
	v_pk_mul_f32 v[80:81], v[58:59], v[70:71] op_sel_hi:[1,0]
	v_pk_mul_f32 v[82:83], v[60:61], v[70:71] op_sel_hi:[1,0]
	s_waitcnt vmcnt(12)
	v_pk_mul_f32 v[76:77], v[74:75], v[180:181]
	v_pk_mul_f32 v[78:79], v[72:73], v[182:183]
	v_or_b32_e32 v251, 16, v161
	v_cndmask_b32_e64 v216, v251, v71, s[40:41]
	v_lshlrev_b32_e32 v216, 4, v216
	v_cndmask_b32_e32 v216, 0, v216, vcc
	v_lshlrev_b32_e32 v216, 2, v216
	global_load_dwordx4 v[180:183], v216, s[22:23]
	global_load_dwordx4 v[212:215], v216, s[22:23] offset:16
	global_load_dwordx4 v[224:227], v[140:141], off
	global_load_dwordx4 v[228:231], v[138:139], off offset:16
	global_load_dwordx4 v[232:235], v216, s[22:23] offset:32
	global_load_dwordx4 v[236:239], v216, s[22:23] offset:48
	global_load_dwordx4 v[218:221], v[140:141], off offset:16
	s_waitcnt vmcnt(13)
	v_mov_b32_e32 v84, v176
	s_waitcnt vmcnt(12)
	v_pk_mul_f32 v[60:61], v[82:83], v[186:187]
	v_pk_mul_f32 v[58:59], v[80:81], v[184:185]
	v_mov_b32_e32 v80, v172
	v_mov_b32_e32 v81, v174
	v_mov_b32_e32 v85, v178
	v_mov_b32_e32 v178, v177
	v_mov_b32_e32 v174, v173
	v_pk_mul_f32 v[82:83], v[80:81], v[58:59]
	v_pk_mul_f32 v[88:89], v[84:85], v[60:61]
	v_pk_mul_f32 v[58:59], v[174:175], v[58:59]
	v_pk_mul_f32 v[60:61], v[178:179], v[60:61]
	v_pk_fma_f32 v[58:59], v[76:77], v[80:81], v[58:59] neg_lo:[0,0,1] neg_hi:[0,0,1]
	v_pk_fma_f32 v[60:61], v[78:79], v[84:85], v[60:61] neg_lo:[0,0,1] neg_hi:[0,0,1]
	v_pk_fma_f32 v[72:73], v[78:79], v[178:179], v[88:89]
	v_pk_fma_f32 v[62:63], v[76:77], v[174:175], v[82:83]
	v_cvt_pk_bf16_f32 v240, v58, v59
	v_cvt_pk_bf16_f32 v241, v60, v61
	v_cvt_pk_bf16_f32 v244, v62, v63
	v_cvt_pk_bf16_f32 v245, v72, v73
	v_pk_mul_f32 v[58:59], v[56:57], v[70:71] op_sel_hi:[1,0]
	v_pk_mul_f32 v[60:61], v[54:55], v[70:71] op_sel_hi:[1,0]
	global_load_dwordx4 v[172:175], v[138:139], off
	v_pk_mul_f32 v[72:73], v[50:51], v[70:71] op_sel_hi:[1,0]
	v_pk_mul_f32 v[74:75], v[52:53], v[70:71] op_sel_hi:[1,0]
	s_waitcnt vmcnt(12)
	v_pk_mul_f32 v[62:63], v[60:61], v[188:189]
	v_pk_mul_f32 v[64:65], v[58:59], v[190:191]
	s_waitcnt vmcnt(10)
	v_mov_b32_e32 v76, v196
	s_waitcnt vmcnt(9)
	v_pk_mul_f32 v[52:53], v[74:75], v[202:203]
	v_pk_mul_f32 v[50:51], v[72:73], v[200:201]
	v_mov_b32_e32 v72, v192
	v_mov_b32_e32 v73, v194
	v_mov_b32_e32 v77, v198
	v_mov_b32_e32 v198, v197
	v_mov_b32_e32 v194, v193
	v_pk_mul_f32 v[74:75], v[72:73], v[50:51]
	v_pk_mul_f32 v[78:79], v[76:77], v[52:53]
	v_pk_mul_f32 v[50:51], v[194:195], v[50:51]
	v_pk_mul_f32 v[52:53], v[198:199], v[52:53]
	v_pk_fma_f32 v[50:51], v[62:63], v[72:73], v[50:51] neg_lo:[0,0,1] neg_hi:[0,0,1]
	v_pk_fma_f32 v[52:53], v[64:65], v[76:77], v[52:53] neg_lo:[0,0,1] neg_hi:[0,0,1]
	v_pk_fma_f32 v[58:59], v[64:65], v[198:199], v[78:79]
	v_pk_fma_f32 v[54:55], v[62:63], v[194:195], v[74:75]
	v_cvt_pk_bf16_f32 v242, v50, v51
	v_cvt_pk_bf16_f32 v243, v52, v53
	global_store_dwordx4 v[68:69], v[240:243], off
	v_cvt_pk_bf16_f32 v246, v54, v55
	v_cvt_pk_bf16_f32 v247, v58, v59
	global_store_dwordx4 v[66:67], v[244:247], off
.LBB0_679:
	s_or_b64 exec, exec, s[2:3]
	v_mul_f32_e32 v50, v38, v38
	v_mul_f32_e32 v51, v39, v39
	v_fmac_f32_e32 v50, v46, v46
	v_fmac_f32_e32 v51, v47, v47
	v_fmac_f32_e32 v50, v42, v42
	v_fmac_f32_e32 v51, v43, v43
	v_fmac_f32_e32 v50, v34, v34
	v_fmac_f32_e32 v51, v35, v35
	v_add_f32_e32 v50, v50, v51
	v_mul_f32_e32 v51, v40, v40
	v_fmac_f32_e32 v51, v48, v48
	v_fmac_f32_e32 v51, v44, v44
	v_fmac_f32_e32 v51, v36, v36
	v_add_f32_e32 v50, v51, v50
	v_mul_f32_e32 v51, v41, v41
	v_fmac_f32_e32 v51, v49, v49
	v_fmac_f32_e32 v51, v45, v45
	v_fmac_f32_e32 v51, v37, v37
	v_add_f32_e32 v50, v51, v50
	ds_swizzle_b32 v51, v50 offset:swizzle(SWAP,16)
	s_waitcnt lgkmcnt(0)
	v_add_f32_e32 v54, v50, v51
	v_mov_b32_e32 v55, v54
	s_nop 1
	v_permlane32_swap_b32_e32 v54, v55
	s_and_saveexec_b64 s[2:3], s[20:21]
	v_add_u32_e32 v50, 0x90, v160
	v_add_f32_e32 v54, v54, v55
	v_mad_u64_u32 v[50:51], s[42:43], s26, v50, v[142:143]
	v_fmaak_f32 v54, v159, v54, 0x358637bd
	v_cmp_gt_f32_e64 s[42:43], s88, v54
	v_mul_f32_e32 v55, 0x4b800000, v54
	v_mov_b32_e32 v51, v0
	v_cndmask_b32_e64 v54, v54, v55, s[42:43]
	v_rsq_f32_e32 v54, v54
	v_lshl_add_u64 v[52:53], v[50:51], 1, s[60:61]
	s_lshl_b32 s54, s16, 1
	v_lshl_add_u64 v[50:51], v[52:53], 0, s[54:55]
	v_mul_f32_e32 v55, 0x45800000, v54
	v_cndmask_b32_e64 v54, v54, v55, s[42:43]
	v_mul_f32_e32 v54, v143, v54
	v_cndmask_b32_e64 v54, v54, 1.0, s[50:51]
	v_pk_mul_f32 v[56:57], v[48:49], v[54:55] op_sel_hi:[1,0]
	v_pk_mul_f32 v[58:59], v[46:47], v[54:55] op_sel_hi:[1,0]
	v_pk_mul_f32 v[64:65], v[42:43], v[54:55] op_sel_hi:[1,0]
	v_pk_mul_f32 v[66:67], v[44:45], v[54:55] op_sel_hi:[1,0]
	s_waitcnt vmcnt(10)
; template <int K> __device__ __forceinline__ float swz(float v) { return __int_as_float(__builtin_amdgcn_ds_swizzle(__float_as_int(v), (K << 10) | 0x1f)); }
; __device__ __forceinline__ float x32_sum(float v) { auto r = __builtin_amdgcn_permlane32_swap(__float_as_uint(v), __float_as_uint(v), false, false); return __uint_as_float(r[0]) + __uint_as_float(r[1]); }
;     __device__ __forceinline__ void operator()(const f32x4 (&acc)[2][2][4][2], const Unit& u, int wr, int wc, int, int) const {
;     ...
; #pragma unroll
;         for (int ai = 0; ai < 2; ++ai)
; #pragma unroll
;             for (int m = 0; m < 4; ++m) {
;                 const int row = rowb + ai * HALF + m * 16;
;                 float ss = 0.f;
; #pragma unroll
;                 for (int j = 0; j < 4; ++j) ss += acc[ai][0][m][0][j] * acc[ai][0][m][0][j] + acc[ai][0][m][1][j] * acc[ai][0][m][1][j] + acc[ai][1][m][0][j] * acc[ai][1][m][0][j] + acc[ai][1][m][1][j] * acc[ai][1][m][1][j];
;                 ss += ::swz<16>(ss); ss = ::x32_sum(ss);
;                 float rs = rsqrtf(ss * inv_cnt + 1e-6f) * sc; rs = is_v ? 1.0f : rs;
;                 const int pos = row & 2047, pp = rot ? ((fq & 1) ? (pos & 63) : (pos >> 6)) : 0;
;                 const float* rt = rope + pp * 16;
;                 bf16_t* dst = obase + (unsigned)(row * ostride + ocol);
; #pragma unroll
;                 for (int n = 0; n < 2; ++n) {
;                     const f32x4 g1 = *(const f32x4*)(g + 4 * n), g2 = *(const f32x4*)(g + sbj + 4 * n);
;                     const f32x4 t0 = *(const f32x4*)(rt + 8 * n), t1 = *(const f32x4*)(rt + 8 * n + 4);
;                     const f32x4 c = (f32x4){t0[0], t0[2], t1[0], t1[2]}, s = (f32x4){t0[1], t0[3], t1[1], t1[3]};
;                     const f32x4 a1 = acc[ai][0][m][n] * rs * g1, a2 = acc[ai][1][m][n] * rs * g2;
;                     const f32x4 o1 = a1 * c - a2 * s, o2 = a1 * s + a2 * c;
;                     if (st_ok) { u32x2 w; w.x = cvt_pk_bf16(o1[0], o1[1]); w.y = cvt_pk_bf16(o1[2], o1[3]); *(u32x2*)(dst + 4 * n) = w;
;                         w.x = cvt_pk_bf16(o2[0], o2[1]); w.y = cvt_pk_bf16(o2[2], o2[3]); *(u32x2*)(dst + sbj + 4 * n) = w; }
;                 }
;                 asm volatile("" ::: "memory");
;             }
	v_pk_mul_f32 v[60:61], v[58:59], v[204:205]
	v_pk_mul_f32 v[62:63], v[56:57], v[206:207]
	v_or_b32_e32 v248, 32, v161
	v_cndmask_b32_e64 v249, v248, v71, s[40:41]
	v_lshlrev_b32_e32 v249, 4, v249
	v_cndmask_b32_e32 v249, 0, v249, vcc
	v_lshlrev_b32_e32 v249, 2, v249
	global_load_dwordx4 v[176:179], v249, s[22:23]
	global_load_dwordx4 v[184:187], v249, s[22:23] offset:16
	global_load_dwordx4 v[188:191], v[140:141], off
	global_load_dwordx4 v[192:195], v[138:139], off offset:16
	global_load_dwordx4 v[196:199], v249, s[22:23] offset:32
	global_load_dwordx4 v[200:203], v249, s[22:23] offset:48
	global_load_dwordx4 v[204:207], v[140:141], off offset:16
	s_waitcnt vmcnt(15)
	v_mov_b32_e32 v68, v212
	s_waitcnt vmcnt(14)
	v_pk_mul_f32 v[44:45], v[66:67], v[226:227]
	v_pk_mul_f32 v[42:43], v[64:65], v[224:225]
	v_mov_b32_e32 v64, v180
	v_mov_b32_e32 v65, v182
	v_mov_b32_e32 v69, v214
	v_mov_b32_e32 v214, v213
	v_mov_b32_e32 v182, v181
	v_pk_mul_f32 v[66:67], v[64:65], v[42:43]
	v_pk_mul_f32 v[72:73], v[68:69], v[44:45]
	v_pk_mul_f32 v[42:43], v[182:183], v[42:43]
	v_pk_mul_f32 v[44:45], v[214:215], v[44:45]
	v_pk_fma_f32 v[42:43], v[60:61], v[64:65], v[42:43] neg_lo:[0,0,1] neg_hi:[0,0,1]
	v_pk_fma_f32 v[44:45], v[62:63], v[68:69], v[44:45] neg_lo:[0,0,1] neg_hi:[0,0,1]
	v_pk_fma_f32 v[56:57], v[62:63], v[214:215], v[72:73]
	v_pk_fma_f32 v[46:47], v[60:61], v[182:183], v[66:67]
	v_cvt_pk_bf16_f32 v240, v42, v43
	v_cvt_pk_bf16_f32 v241, v44, v45
	v_cvt_pk_bf16_f32 v244, v46, v47
	v_cvt_pk_bf16_f32 v245, v56, v57
	v_pk_mul_f32 v[42:43], v[40:41], v[54:55] op_sel_hi:[1,0]
	v_pk_mul_f32 v[44:45], v[38:39], v[54:55] op_sel_hi:[1,0]
	global_load_dwordx4 v[180:183], v[138:139], off
	v_pk_mul_f32 v[56:57], v[34:35], v[54:55] op_sel_hi:[1,0]
	s_waitcnt vmcnt(14)
	v_pk_mul_f32 v[46:47], v[44:45], v[228:229]
	v_pk_mul_f32 v[48:49], v[42:43], v[230:231]
	v_pk_mul_f32 v[54:55], v[36:37], v[54:55] op_sel_hi:[1,0]
	s_waitcnt vmcnt(12)
	v_mov_b32_e32 v58, v236
	v_mov_b32_e32 v59, v238
	s_waitcnt vmcnt(11)
	v_pk_mul_f32 v[36:37], v[54:55], v[220:221]
	v_pk_mul_f32 v[34:35], v[56:57], v[218:219]
	v_mov_b32_e32 v54, v232
	v_mov_b32_e32 v55, v234
	v_mov_b32_e32 v238, v237
	v_mov_b32_e32 v234, v233
	v_pk_mul_f32 v[56:57], v[54:55], v[34:35]
	v_pk_mul_f32 v[60:61], v[58:59], v[36:37]
	v_pk_mul_f32 v[34:35], v[234:235], v[34:35]
	v_pk_mul_f32 v[36:37], v[238:239], v[36:37]
	v_pk_fma_f32 v[34:35], v[46:47], v[54:55], v[34:35] neg_lo:[0,0,1] neg_hi:[0,0,1]
	v_pk_fma_f32 v[36:37], v[48:49], v[58:59], v[36:37] neg_lo:[0,0,1] neg_hi:[0,0,1]
	v_pk_fma_f32 v[42:43], v[48:49], v[238:239], v[60:61]
	v_pk_fma_f32 v[38:39], v[46:47], v[234:235], v[56:57]
	v_cvt_pk_bf16_f32 v242, v34, v35
	v_cvt_pk_bf16_f32 v243, v36, v37
	global_store_dwordx4 v[52:53], v[240:243], off
	v_cvt_pk_bf16_f32 v246, v38, v39
	v_cvt_pk_bf16_f32 v247, v42, v43
	global_store_dwordx4 v[50:51], v[244:247], off
.LBB0_681:
	s_or_b64 exec, exec, s[2:3]
	v_mul_f32_e32 v34, v22, v22
	v_mul_f32_e32 v35, v23, v23
	v_fmac_f32_e32 v34, v30, v30
	v_fmac_f32_e32 v35, v31, v31
	v_fmac_f32_e32 v34, v26, v26
	v_fmac_f32_e32 v35, v27, v27
	v_fmac_f32_e32 v34, v18, v18
	v_fmac_f32_e32 v35, v19, v19
	v_add_f32_e32 v34, v34, v35
	v_mul_f32_e32 v35, v24, v24
	v_fmac_f32_e32 v35, v32, v32
	v_fmac_f32_e32 v35, v28, v28
	v_fmac_f32_e32 v35, v20, v20
	v_add_f32_e32 v34, v35, v34
	v_mul_f32_e32 v35, v25, v25
	v_fmac_f32_e32 v35, v33, v33
	v_fmac_f32_e32 v35, v29, v29
	v_fmac_f32_e32 v35, v21, v21
	v_add_f32_e32 v34, v35, v34
	ds_swizzle_b32 v35, v34 offset:swizzle(SWAP,16)
	s_waitcnt lgkmcnt(0)
	v_add_f32_e32 v38, v34, v35
	v_mov_b32_e32 v39, v38
	s_nop 1
	v_permlane32_swap_b32_e32 v38, v39
	s_and_saveexec_b64 s[2:3], s[20:21]
	v_add_u32_e32 v34, 0xa0, v160
	v_add_f32_e32 v38, v38, v39
	v_mad_u64_u32 v[34:35], s[42:43], s26, v34, v[142:143]
	v_fmaak_f32 v38, v159, v38, 0x358637bd
	v_cmp_gt_f32_e64 s[42:43], s88, v38
	v_mul_f32_e32 v39, 0x4b800000, v38
	v_mov_b32_e32 v35, v0
	v_cndmask_b32_e64 v38, v38, v39, s[42:43]
	v_rsq_f32_e32 v38, v38
	v_lshl_add_u64 v[36:37], v[34:35], 1, s[60:61]
	s_lshl_b32 s54, s16, 1
	v_lshl_add_u64 v[34:35], v[36:37], 0, s[54:55]
	v_mul_f32_e32 v39, 0x45800000, v38
	v_cndmask_b32_e64 v38, v38, v39, s[42:43]
	v_mul_f32_e32 v38, v143, v38
	v_cndmask_b32_e64 v38, v38, 1.0, s[50:51]
	v_pk_mul_f32 v[40:41], v[32:33], v[38:39] op_sel_hi:[1,0]
	v_pk_mul_f32 v[42:43], v[30:31], v[38:39] op_sel_hi:[1,0]
	v_pk_mul_f32 v[48:49], v[26:27], v[38:39] op_sel_hi:[1,0]
	v_pk_mul_f32 v[50:51], v[28:29], v[38:39] op_sel_hi:[1,0]
	s_waitcnt vmcnt(12)
	v_pk_mul_f32 v[44:45], v[42:43], v[172:173]
	v_pk_mul_f32 v[46:47], v[40:41], v[174:175]
	v_or_b32_e32 v251, 48, v161
	v_cndmask_b32_e64 v216, v251, v71, s[40:41]
	v_lshlrev_b32_e32 v216, 4, v216
	v_cndmask_b32_e32 v216, 0, v216, vcc
	v_lshlrev_b32_e32 v216, 2, v216
	global_load_dwordx4 v[172:175], v216, s[22:23]
	global_load_dwordx4 v[212:215], v216, s[22:23] offset:16
	global_load_dwordx4 v[224:227], v[140:141], off
	global_load_dwordx4 v[228:231], v[138:139], off offset:16
	global_load_dwordx4 v[232:235], v216, s[22:23] offset:32
	global_load_dwordx4 v[236:239], v216, s[22:23] offset:48
	global_load_dwordx4 v[218:221], v[140:141], off offset:16
	s_waitcnt vmcnt(15)
	v_mov_b32_e32 v52, v184
	s_waitcnt vmcnt(14)
; template <int K> __device__ __forceinline__ float swz(float v) { return __int_as_float(__builtin_amdgcn_ds_swizzle(__float_as_int(v), (K << 10) | 0x1f)); }
; __device__ __forceinline__ float x32_sum(float v) { auto r = __builtin_amdgcn_permlane32_swap(__float_as_uint(v), __float_as_uint(v), false, false); return __uint_as_float(r[0]) + __uint_as_float(r[1]); }
;     __device__ __forceinline__ void operator()(const f32x4 (&acc)[2][2][4][2], const Unit& u, int wr, int wc, int, int) const {
;     ...
; #pragma unroll
;         for (int ai = 0; ai < 2; ++ai)
; #pragma unroll
;             for (int m = 0; m < 4; ++m) {
;                 const int row = rowb + ai * HALF + m * 16;
;                 float ss = 0.f;
; #pragma unroll
;                 for (int j = 0; j < 4; ++j) ss += acc[ai][0][m][0][j] * acc[ai][0][m][0][j] + acc[ai][0][m][1][j] * acc[ai][0][m][1][j] + acc[ai][1][m][0][j] * acc[ai][1][m][0][j] + acc[ai][1][m][1][j] * acc[ai][1][m][1][j];
;                 ss += ::swz<16>(ss); ss = ::x32_sum(ss);
;                 float rs = rsqrtf(ss * inv_cnt + 1e-6f) * sc; rs = is_v ? 1.0f : rs;
;                 const int pos = row & 2047, pp = rot ? ((fq & 1) ? (pos & 63) : (pos >> 6)) : 0;
;                 const float* rt = rope + pp * 16;
;                 bf16_t* dst = obase + (unsigned)(row * ostride + ocol);
; #pragma unroll
;                 for (int n = 0; n < 2; ++n) {
;                     const f32x4 g1 = *(const f32x4*)(g + 4 * n), g2 = *(const f32x4*)(g + sbj + 4 * n);
;                     const f32x4 t0 = *(const f32x4*)(rt + 8 * n), t1 = *(const f32x4*)(rt + 8 * n + 4);
;                     const f32x4 c = (f32x4){t0[0], t0[2], t1[0], t1[2]}, s = (f32x4){t0[1], t0[3], t1[1], t1[3]};
;                     const f32x4 a1 = acc[ai][0][m][n] * rs * g1, a2 = acc[ai][1][m][n] * rs * g2;
;                     const f32x4 o1 = a1 * c - a2 * s, o2 = a1 * s + a2 * c;
;                     if (st_ok) { u32x2 w; w.x = cvt_pk_bf16(o1[0], o1[1]); w.y = cvt_pk_bf16(o1[2], o1[3]); *(u32x2*)(dst + 4 * n) = w;
;                         w.x = cvt_pk_bf16(o2[0], o2[1]); w.y = cvt_pk_bf16(o2[2], o2[3]); *(u32x2*)(dst + sbj + 4 * n) = w; }
;                 }
;                 asm volatile("" ::: "memory");
;             }
	v_pk_mul_f32 v[28:29], v[50:51], v[190:191]
	v_pk_mul_f32 v[26:27], v[48:49], v[188:189]
	v_mov_b32_e32 v48, v176
	v_mov_b32_e32 v49, v178
	v_mov_b32_e32 v53, v186
	v_mov_b32_e32 v186, v185
	v_mov_b32_e32 v178, v177
	v_pk_mul_f32 v[50:51], v[48:49], v[26:27]
	v_pk_mul_f32 v[54:55], v[52:53], v[28:29]
	v_pk_mul_f32 v[26:27], v[178:179], v[26:27]
	v_pk_mul_f32 v[28:29], v[186:187], v[28:29]
	v_pk_fma_f32 v[26:27], v[44:45], v[48:49], v[26:27] neg_lo:[0,0,1] neg_hi:[0,0,1]
	v_pk_fma_f32 v[28:29], v[46:47], v[52:53], v[28:29] neg_lo:[0,0,1] neg_hi:[0,0,1]
	v_pk_fma_f32 v[40:41], v[46:47], v[186:187], v[54:55]
	v_pk_fma_f32 v[30:31], v[44:45], v[178:179], v[50:51]
	v_cvt_pk_bf16_f32 v240, v26, v27
	v_cvt_pk_bf16_f32 v241, v28, v29
	v_cvt_pk_bf16_f32 v244, v30, v31
	v_cvt_pk_bf16_f32 v245, v40, v41
	v_pk_mul_f32 v[26:27], v[24:25], v[38:39] op_sel_hi:[1,0]
	v_pk_mul_f32 v[28:29], v[22:23], v[38:39] op_sel_hi:[1,0]
	v_pk_mul_f32 v[40:41], v[18:19], v[38:39] op_sel_hi:[1,0]
	s_waitcnt vmcnt(13)
	v_pk_mul_f32 v[30:31], v[28:29], v[192:193]
	v_pk_mul_f32 v[32:33], v[26:27], v[194:195]
	v_pk_mul_f32 v[38:39], v[20:21], v[38:39] op_sel_hi:[1,0]
	s_waitcnt vmcnt(11)
	v_mov_b32_e32 v42, v200
	v_mov_b32_e32 v43, v202
	s_waitcnt vmcnt(10)
	v_pk_mul_f32 v[20:21], v[38:39], v[206:207]
	v_pk_mul_f32 v[18:19], v[40:41], v[204:205]
	v_mov_b32_e32 v38, v196
	v_mov_b32_e32 v39, v198
	v_mov_b32_e32 v202, v201
	v_mov_b32_e32 v198, v197
	v_pk_mul_f32 v[40:41], v[38:39], v[18:19]
	v_pk_mul_f32 v[44:45], v[42:43], v[20:21]
	v_pk_mul_f32 v[18:19], v[198:199], v[18:19]
	v_pk_mul_f32 v[20:21], v[202:203], v[20:21]
	v_pk_fma_f32 v[18:19], v[30:31], v[38:39], v[18:19] neg_lo:[0,0,1] neg_hi:[0,0,1]
	v_pk_fma_f32 v[20:21], v[32:33], v[42:43], v[20:21] neg_lo:[0,0,1] neg_hi:[0,0,1]
	v_pk_fma_f32 v[26:27], v[32:33], v[202:203], v[44:45]
	v_pk_fma_f32 v[22:23], v[30:31], v[198:199], v[40:41]
	v_cvt_pk_bf16_f32 v242, v18, v19
	v_cvt_pk_bf16_f32 v243, v20, v21
	global_store_dwordx4 v[36:37], v[240:243], off
	v_cvt_pk_bf16_f32 v246, v22, v23
	v_cvt_pk_bf16_f32 v247, v26, v27
	global_store_dwordx4 v[34:35], v[244:247], off
.LBB0_683:
	s_or_b64 exec, exec, s[2:3]
	v_mul_f32_e32 v18, v6, v6
	v_mul_f32_e32 v19, v7, v7
	v_fmac_f32_e32 v18, v14, v14
	v_fmac_f32_e32 v19, v15, v15
	v_fmac_f32_e32 v18, v10, v10
	v_fmac_f32_e32 v19, v11, v11
	v_fmac_f32_e32 v18, v2, v2
	v_fmac_f32_e32 v19, v3, v3
	v_add_f32_e32 v18, v18, v19
	v_mul_f32_e32 v19, v8, v8
	v_fmac_f32_e32 v19, v16, v16
	v_fmac_f32_e32 v19, v12, v12
	v_fmac_f32_e32 v19, v4, v4
	v_add_f32_e32 v18, v19, v18
	v_mul_f32_e32 v19, v9, v9
	v_fmac_f32_e32 v19, v17, v17
	v_fmac_f32_e32 v19, v13, v13
	v_fmac_f32_e32 v19, v5, v5
	v_add_f32_e32 v18, v19, v18
	ds_swizzle_b32 v19, v18 offset:swizzle(SWAP,16)
	s_waitcnt lgkmcnt(0)
	v_add_f32_e32 v22, v18, v19
	v_mov_b32_e32 v23, v22
	s_nop 1
	v_permlane32_swap_b32_e32 v22, v23
	s_and_saveexec_b64 s[2:3], s[20:21]
	v_add_f32_e32 v22, v22, v23
	v_fmaak_f32 v22, v159, v22, 0x358637bd
	v_cmp_gt_f32_e64 s[42:43], s88, v22
	v_mul_f32_e32 v23, 0x4b800000, v22
	v_add_u32_e32 v18, 0xb0, v160
	v_cndmask_b32_e64 v22, v22, v23, s[42:43]
	v_rsq_f32_e32 v22, v22
	v_mad_u64_u32 v[18:19], s[20:21], s26, v18, v[142:143]
	v_mov_b32_e32 v19, v0
	v_mul_f32_e32 v23, 0x45800000, v22
	v_cndmask_b32_e64 v22, v22, v23, s[42:43]
	v_mul_f32_e32 v22, v143, v22
	v_cndmask_b32_e64 v22, v22, 1.0, s[50:51]
	v_pk_mul_f32 v[24:25], v[16:17], v[22:23] op_sel_hi:[1,0]
	v_pk_mul_f32 v[26:27], v[14:15], v[22:23] op_sel_hi:[1,0]
	v_pk_mul_f32 v[32:33], v[10:11], v[22:23] op_sel_hi:[1,0]
	v_pk_mul_f32 v[34:35], v[12:13], v[22:23] op_sel_hi:[1,0]
	v_lshl_add_u64 v[20:21], v[18:19], 1, s[60:61]
	s_lshl_b32 s54, s16, 1
	v_lshl_add_u64 v[18:19], v[20:21], 0, s[54:55]
	s_waitcnt vmcnt(11)
	v_pk_mul_f32 v[28:29], v[26:27], v[180:181]
	v_pk_mul_f32 v[30:31], v[24:25], v[182:183]
	s_waitcnt vmcnt(7)
	v_mov_b32_e32 v36, v212
	s_waitcnt vmcnt(6)
	v_pk_mul_f32 v[12:13], v[34:35], v[226:227]
	v_pk_mul_f32 v[10:11], v[32:33], v[224:225]
	v_mov_b32_e32 v32, v172
	v_mov_b32_e32 v33, v174
	v_mov_b32_e32 v37, v214
	v_mov_b32_e32 v214, v213
	v_mov_b32_e32 v174, v173
	v_pk_mul_f32 v[34:35], v[32:33], v[10:11]
	v_pk_mul_f32 v[38:39], v[36:37], v[12:13]
	v_pk_mul_f32 v[10:11], v[174:175], v[10:11]
	v_pk_mul_f32 v[12:13], v[214:215], v[12:13]
	v_pk_fma_f32 v[10:11], v[28:29], v[32:33], v[10:11] neg_lo:[0,0,1] neg_hi:[0,0,1]
	v_pk_fma_f32 v[12:13], v[30:31], v[36:37], v[12:13] neg_lo:[0,0,1] neg_hi:[0,0,1]
	v_pk_fma_f32 v[24:25], v[30:31], v[214:215], v[38:39]
	v_pk_fma_f32 v[14:15], v[28:29], v[174:175], v[34:35]
	v_cvt_pk_bf16_f32 v240, v10, v11
	v_cvt_pk_bf16_f32 v241, v12, v13
	v_cvt_pk_bf16_f32 v244, v14, v15
	v_cvt_pk_bf16_f32 v245, v24, v25
	v_pk_mul_f32 v[10:11], v[8:9], v[22:23] op_sel_hi:[1,0]
	v_pk_mul_f32 v[12:13], v[6:7], v[22:23] op_sel_hi:[1,0]
	v_pk_mul_f32 v[24:25], v[2:3], v[22:23] op_sel_hi:[1,0]
	s_waitcnt vmcnt(5)
	v_pk_mul_f32 v[14:15], v[12:13], v[228:229]
	v_pk_mul_f32 v[16:17], v[10:11], v[230:231]
	v_pk_mul_f32 v[22:23], v[4:5], v[22:23] op_sel_hi:[1,0]
	s_waitcnt vmcnt(3)
	v_mov_b32_e32 v26, v236
	v_mov_b32_e32 v27, v238
	s_waitcnt vmcnt(2)
	v_pk_mul_f32 v[4:5], v[22:23], v[220:221]
	v_pk_mul_f32 v[2:3], v[24:25], v[218:219]
	v_mov_b32_e32 v22, v232
	v_mov_b32_e32 v23, v234
	v_mov_b32_e32 v238, v237
	v_mov_b32_e32 v234, v233
	v_pk_mul_f32 v[24:25], v[22:23], v[2:3]
	v_pk_mul_f32 v[28:29], v[26:27], v[4:5]
	v_pk_mul_f32 v[2:3], v[234:235], v[2:3]
	v_pk_mul_f32 v[4:5], v[238:239], v[4:5]
	v_pk_fma_f32 v[2:3], v[14:15], v[22:23], v[2:3] neg_lo:[0,0,1] neg_hi:[0,0,1]
	v_pk_fma_f32 v[4:5], v[16:17], v[26:27], v[4:5] neg_lo:[0,0,1] neg_hi:[0,0,1]
	v_pk_fma_f32 v[10:11], v[16:17], v[238:239], v[28:29]
	v_pk_fma_f32 v[6:7], v[14:15], v[234:235], v[24:25]
	v_cvt_pk_bf16_f32 v242, v2, v3
	v_cvt_pk_bf16_f32 v243, v4, v5
	global_store_dwordx4 v[20:21], v[240:243], off
	v_cvt_pk_bf16_f32 v246, v6, v7
	v_cvt_pk_bf16_f32 v247, v10, v11
	global_store_dwordx4 v[18:19], v[244:247], off
	s_branch .LBB0_650

;     __device__ __forceinline__ void operator()(const f32x4 (&acc)[2][2][4][2], const Unit& u, int wr, int wc, int fr, int fq) const {
;     ...
;         const bool isctx = u.pm >= 128;
;         const float* inb = isctx ? in_ctx : in_lat; float* outb = isctx ? out_ctx : out_lat;
;         const int pml = isctx ? u.pm - 128 : u.pm;
;         const float* gp = gate + (size_t)(isctx ? 16 : (u.pm >> 3)) * 6144;
;         const int row0 = pml * BM + wr * 64 + fr, col0 = u.pn * BM + wc * 32 + 4 * fq;
;         f32x4 gv[2][2];
; #pragma unroll
;         for (int bj = 0; bj < 2; ++bj)
; #pragma unroll
;             for (int n = 0; n < 2; ++n) gv[bj][n] = *(const f32x4*)(gp + col0 + bj * HALF + n * 16);
; #pragma unroll
;         for (int ai = 0; ai < 2; ++ai)
; #pragma unroll
;             for (int m = 0; m < 4; ++m) { const size_t ro = (size_t)(row0 + ai * HALF + m * 16) * 1024 + col0;
; #pragma unroll
;                 for (int bj = 0; bj < 2; ++bj)
; #pragma unroll
;                     for (int n = 0; n < 2; ++n) { const f32x4 x = *(const f32x4*)(inb + ro + bj * HALF + n * 16);
;                         *(f32x4*)(outb + ro + bj * HALF + n * 16) = x + gv[bj][n] * acc[ai][bj][m][n]; } }
.LBB0_979:
	s_and_b64 s[2:3], exec, s[26:27]
	v_readlane_b32 s2, v255, 39
	v_readlane_b32 s16, v255, 41
	v_readlane_b32 s3, v255, 40
	v_readlane_b32 s17, v255, 42
	s_cselect_b32 s3, s3, s17
	s_cselect_b32 s2, s2, s16
	s_cselect_b32 s17, s65, s43
	s_cselect_b32 s16, s64, s42
	s_lshl_b64 s[18:19], s[28:29], 2
	s_add_u32 s18, s52, s18
	s_addc_u32 s19, s53, s19
	s_lshl_b32 s5, s20, 8
	s_add_i32 s21, s5, 0xffff8000
	s_and_b64 s[26:27], exec, s[26:27]
	s_cselect_b32 s5, s21, s5
	v_add_u32_e32 v174, s5, v160
	v_lshl_or_b32 v172, s11, 8, v161
	v_ashrrev_i32_e32 v175, 31, v174
	v_ashrrev_i32_e32 v173, 31, v172
	v_lshlrev_b64 v[146:147], 10, v[174:175]
	v_lshl_add_u64 v[146:147], v[146:147], 0, v[172:173]
	v_lshlrev_b64 v[170:171], 2, v[146:147]
	v_lshl_add_u64 v[130:131], v[172:173], 2, s[18:19]
	v_lshl_add_u64 v[150:151], s[2:3], 0, v[170:171]
	global_load_dwordx4 v[142:145], v[130:131], off
	global_load_dwordx4 v[138:141], v[130:131], off offset:64
	global_load_dwordx4 v[134:137], v[130:131], off offset:512
	s_nop 0
	global_load_dwordx4 v[130:133], v[130:131], off offset:576
	v_lshl_add_u64 v[152:153], s[16:17], 0, v[170:171]
	s_mov_b64 s[98:99], 0x10000
	v_lshl_add_u64 v[176:177], v[150:151], 0, s[98:99]
	v_lshl_add_u64 v[178:179], v[152:153], 0, s[98:99]
	s_mov_b64 s[98:99], 0x20000
	v_lshl_add_u64 v[180:181], v[150:151], 0, s[98:99]
	v_lshl_add_u64 v[182:183], v[152:153], 0, s[98:99]
	s_mov_b64 s[98:99], 0x30000
	v_lshl_add_u64 v[184:185], v[150:151], 0, s[98:99]
	v_lshl_add_u64 v[186:187], v[152:153], 0, s[98:99]
	s_mov_b64 s[98:99], 0x80000
	v_lshl_add_u64 v[188:189], v[150:151], 0, s[98:99]
	v_lshl_add_u64 v[190:191], v[152:153], 0, s[98:99]
	s_mov_b64 s[98:99], 0x90000
	v_lshl_add_u64 v[192:193], v[150:151], 0, s[98:99]
	v_lshl_add_u64 v[194:195], v[152:153], 0, s[98:99]
	s_mov_b64 s[98:99], 0xa0000
	v_lshl_add_u64 v[196:197], v[150:151], 0, s[98:99]
	v_lshl_add_u64 v[198:199], v[152:153], 0, s[98:99]
	s_mov_b64 s[98:99], 0xb0000
	v_lshl_add_u64 v[200:201], v[150:151], 0, s[98:99]
	v_lshl_add_u64 v[202:203], v[152:153], 0, s[98:99]
	global_load_dwordx4 v[204:207], v[150:151], off
	global_load_dwordx4 v[212:215], v[150:151], off offset:64
	global_load_dwordx4 v[224:227], v[150:151], off offset:512
	global_load_dwordx4 v[228:231], v[150:151], off offset:576
	global_load_dwordx4 v[232:235], v[176:177], off
	global_load_dwordx4 v[236:239], v[176:177], off offset:64
	global_load_dwordx4 v[240:243], v[176:177], off offset:512
	global_load_dwordx4 v[244:247], v[176:177], off offset:576
	global_load_dwordx4 v[248:251], v[180:181], off
	global_load_dwordx4 v[218:221], v[180:181], off offset:64
	global_load_dwordx4 v[172:175], v[180:181], off offset:512
	s_waitcnt vmcnt(10)
	v_pk_fma_f32 v[206:207], v[128:129], v[144:145], v[206:207]
	v_pk_fma_f32 v[204:205], v[126:127], v[142:143], v[204:205]
	global_store_dwordx4 v[152:153], v[204:207], off
	global_load_dwordx4 v[126:129], v[180:181], off offset:576
	s_waitcnt vmcnt(11)
	v_pk_fma_f32 v[214:215], v[124:125], v[140:141], v[214:215]
	v_pk_fma_f32 v[212:213], v[122:123], v[138:139], v[212:213]
	global_store_dwordx4 v[152:153], v[212:215], off offset:64
	global_load_dwordx4 v[204:207], v[184:185], off
	global_load_dwordx4 v[122:125], v[184:185], off offset:64
	s_waitcnt vmcnt(13)
	v_pk_fma_f32 v[226:227], v[112:113], v[136:137], v[226:227]
	v_pk_fma_f32 v[224:225], v[110:111], v[134:135], v[224:225]
	global_store_dwordx4 v[152:153], v[224:227], off offset:512
	global_load_dwordx4 v[212:215], v[184:185], off offset:512
	global_load_dwordx4 v[110:113], v[184:185], off offset:576
	s_waitcnt vmcnt(15)
	v_pk_fma_f32 v[230:231], v[104:105], v[132:133], v[230:231]
	v_pk_fma_f32 v[228:229], v[102:103], v[130:131], v[228:229]
	global_store_dwordx4 v[152:153], v[228:231], off offset:576
	global_load_dwordx4 v[224:227], v[188:189], off
	global_load_dwordx4 v[102:105], v[188:189], off offset:64
	s_waitcnt vmcnt(17)
	v_pk_fma_f32 v[234:235], v[120:121], v[144:145], v[234:235]
	v_pk_fma_f32 v[232:233], v[118:119], v[142:143], v[232:233]
	global_store_dwordx4 v[178:179], v[232:235], off
	global_load_dwordx4 v[228:231], v[188:189], off offset:512
	global_load_dwordx4 v[118:121], v[188:189], off offset:576
	s_waitcnt vmcnt(19)
	v_pk_fma_f32 v[238:239], v[116:117], v[140:141], v[238:239]
	v_pk_fma_f32 v[236:237], v[114:115], v[138:139], v[236:237]
	global_store_dwordx4 v[178:179], v[236:239], off offset:64
	global_load_dwordx4 v[232:235], v[192:193], off
	global_load_dwordx4 v[114:117], v[192:193], off offset:64
	s_waitcnt vmcnt(21)
	v_pk_fma_f32 v[242:243], v[96:97], v[136:137], v[242:243]
	v_pk_fma_f32 v[240:241], v[94:95], v[134:135], v[240:241]
	global_store_dwordx4 v[178:179], v[240:243], off offset:512
	global_load_dwordx4 v[236:239], v[192:193], off offset:512
	global_load_dwordx4 v[94:97], v[192:193], off offset:576
	s_waitcnt vmcnt(23)
	v_pk_fma_f32 v[246:247], v[88:89], v[132:133], v[246:247]
	v_pk_fma_f32 v[244:245], v[86:87], v[130:131], v[244:245]
	global_store_dwordx4 v[178:179], v[244:247], off offset:576
	global_load_dwordx4 v[240:243], v[196:197], off
	global_load_dwordx4 v[86:89], v[196:197], off offset:64
	s_waitcnt vmcnt(25)
;     __device__ __forceinline__ void operator()(const f32x4 (&acc)[2][2][4][2], const Unit& u, int wr, int wc, int fr, int fq) const {
;     ...
;         for (int ai = 0; ai < 2; ++ai)
; #pragma unroll
;             for (int m = 0; m < 4; ++m) { const size_t ro = (size_t)(row0 + ai * HALF + m * 16) * 1024 + col0;
; #pragma unroll
;                 for (int bj = 0; bj < 2; ++bj)
; #pragma unroll
;                     for (int n = 0; n < 2; ++n) { const f32x4 x = *(const f32x4*)(inb + ro + bj * HALF + n * 16);
;                         *(f32x4*)(outb + ro + bj * HALF + n * 16) = x + gv[bj][n] * acc[ai][bj][m][n]; } }
	v_pk_fma_f32 v[250:251], v[108:109], v[144:145], v[250:251]
	v_pk_fma_f32 v[248:249], v[106:107], v[142:143], v[248:249]
	global_store_dwordx4 v[182:183], v[248:251], off
	global_load_dwordx4 v[244:247], v[196:197], off offset:512
	global_load_dwordx4 v[106:109], v[196:197], off offset:576
	s_waitcnt vmcnt(27)
	v_pk_fma_f32 v[220:221], v[100:101], v[140:141], v[220:221]
	v_pk_fma_f32 v[218:219], v[98:99], v[138:139], v[218:219]
	global_store_dwordx4 v[182:183], v[218:221], off offset:64
	global_load_dwordx4 v[248:251], v[200:201], off
	global_load_dwordx4 v[98:101], v[200:201], off offset:64
	s_waitcnt vmcnt(29)
	v_pk_fma_f32 v[174:175], v[80:81], v[136:137], v[174:175]
	v_pk_fma_f32 v[172:173], v[78:79], v[134:135], v[172:173]
	global_store_dwordx4 v[182:183], v[172:175], off offset:512
	global_load_dwordx4 v[218:221], v[200:201], off offset:512
	global_load_dwordx4 v[78:81], v[200:201], off offset:576
	s_waitcnt vmcnt(30)
	v_pk_fma_f32 v[128:129], v[76:77], v[132:133], v[128:129]
	v_pk_fma_f32 v[126:127], v[74:75], v[130:131], v[126:127]
	global_store_dwordx4 v[182:183], v[126:129], off offset:576
	s_waitcnt vmcnt(29)
	v_pk_fma_f32 v[206:207], v[92:93], v[144:145], v[206:207]
	v_pk_fma_f32 v[204:205], v[90:91], v[142:143], v[204:205]
	global_store_dwordx4 v[186:187], v[204:207], off
	s_waitcnt vmcnt(29)
	v_pk_fma_f32 v[124:125], v[84:85], v[140:141], v[124:125]
	v_pk_fma_f32 v[122:123], v[82:83], v[138:139], v[122:123]
	global_store_dwordx4 v[186:187], v[122:125], off offset:64
	s_waitcnt vmcnt(28)
	v_pk_fma_f32 v[214:215], v[72:73], v[136:137], v[214:215]
	v_pk_fma_f32 v[212:213], v[70:71], v[134:135], v[212:213]
	global_store_dwordx4 v[186:187], v[212:215], off offset:512
	s_waitcnt vmcnt(28)
	v_pk_fma_f32 v[112:113], v[68:69], v[132:133], v[112:113]
	v_pk_fma_f32 v[110:111], v[66:67], v[130:131], v[110:111]
	global_store_dwordx4 v[186:187], v[110:113], off offset:576
	s_waitcnt vmcnt(27)
	v_pk_fma_f32 v[226:227], v[64:65], v[144:145], v[226:227]
	v_pk_fma_f32 v[224:225], v[62:63], v[142:143], v[224:225]
	global_store_dwordx4 v[190:191], v[224:227], off
	s_waitcnt vmcnt(27)
	v_pk_fma_f32 v[104:105], v[60:61], v[140:141], v[104:105]
	v_pk_fma_f32 v[102:103], v[58:59], v[138:139], v[102:103]
	global_store_dwordx4 v[190:191], v[102:105], off offset:64
	s_waitcnt vmcnt(26)
	v_pk_fma_f32 v[230:231], v[48:49], v[136:137], v[230:231]
	v_pk_fma_f32 v[228:229], v[46:47], v[134:135], v[228:229]
	global_store_dwordx4 v[190:191], v[228:231], off offset:512
	s_waitcnt vmcnt(26)
	v_pk_fma_f32 v[120:121], v[44:45], v[132:133], v[120:121]
	v_pk_fma_f32 v[118:119], v[42:43], v[130:131], v[118:119]
	global_store_dwordx4 v[190:191], v[118:121], off offset:576
	s_waitcnt vmcnt(25)
	v_pk_fma_f32 v[234:235], v[56:57], v[144:145], v[234:235]
	v_pk_fma_f32 v[232:233], v[54:55], v[142:143], v[232:233]
	global_store_dwordx4 v[194:195], v[232:235], off
	s_waitcnt vmcnt(25)
	v_pk_fma_f32 v[116:117], v[52:53], v[140:141], v[116:117]
	v_pk_fma_f32 v[114:115], v[50:51], v[138:139], v[114:115]
	global_store_dwordx4 v[194:195], v[114:117], off offset:64
	s_waitcnt vmcnt(24)
	v_pk_fma_f32 v[238:239], v[32:33], v[136:137], v[238:239]
	v_pk_fma_f32 v[236:237], v[30:31], v[134:135], v[236:237]
	global_store_dwordx4 v[194:195], v[236:239], off offset:512
	s_waitcnt vmcnt(24)
	v_pk_fma_f32 v[96:97], v[28:29], v[132:133], v[96:97]
	v_pk_fma_f32 v[94:95], v[26:27], v[130:131], v[94:95]
	global_store_dwordx4 v[194:195], v[94:97], off offset:576
	s_waitcnt vmcnt(23)
	v_pk_fma_f32 v[242:243], v[40:41], v[144:145], v[242:243]
	v_pk_fma_f32 v[240:241], v[38:39], v[142:143], v[240:241]
	global_store_dwordx4 v[198:199], v[240:243], off
	s_waitcnt vmcnt(23)
	v_pk_fma_f32 v[88:89], v[36:37], v[140:141], v[88:89]
	v_pk_fma_f32 v[86:87], v[34:35], v[138:139], v[86:87]
	global_store_dwordx4 v[198:199], v[86:89], off offset:64
	s_waitcnt vmcnt(22)
	v_pk_fma_f32 v[246:247], v[16:17], v[136:137], v[246:247]
	v_pk_fma_f32 v[244:245], v[14:15], v[134:135], v[244:245]
	global_store_dwordx4 v[198:199], v[244:247], off offset:512
	s_waitcnt vmcnt(22)
	v_pk_fma_f32 v[108:109], v[12:13], v[132:133], v[108:109]
	v_pk_fma_f32 v[106:107], v[10:11], v[130:131], v[106:107]
	global_store_dwordx4 v[198:199], v[106:109], off offset:576
	s_waitcnt vmcnt(21)
	v_pk_fma_f32 v[250:251], v[24:25], v[144:145], v[250:251]
	v_pk_fma_f32 v[248:249], v[22:23], v[142:143], v[248:249]
	global_store_dwordx4 v[202:203], v[248:251], off
	s_waitcnt vmcnt(21)
	v_pk_fma_f32 v[100:101], v[20:21], v[140:141], v[100:101]
	v_pk_fma_f32 v[98:99], v[18:19], v[138:139], v[98:99]
	global_store_dwordx4 v[202:203], v[98:101], off offset:64
	s_waitcnt vmcnt(20)
	v_pk_fma_f32 v[220:221], v[8:9], v[136:137], v[220:221]
	v_pk_fma_f32 v[218:219], v[6:7], v[134:135], v[218:219]
	global_store_dwordx4 v[202:203], v[218:221], off offset:512
	s_waitcnt vmcnt(20)
	v_pk_fma_f32 v[80:81], v[4:5], v[132:133], v[80:81]
	v_pk_fma_f32 v[78:79], v[2:3], v[130:131], v[78:79]
	global_store_dwordx4 v[202:203], v[78:81], off offset:576
	s_mov_b64 s[2:3], 0

;     __device__ __forceinline__ void operator()(const f32x4 (&acc)[2][2][4][2], const Unit& u, int wr, int wc, int fr, int fq) const {
;     ...
;         const bool isctx = u.pm >= 128;
;         const float* inb = isctx ? in_ctx : in_lat; float* outb = isctx ? out_ctx : out_lat;
;         const int pml = isctx ? u.pm - 128 : u.pm;
;         const float* gp = gate + (size_t)(isctx ? 16 : (u.pm >> 3)) * 6144;
;         const int row0 = pml * BM + wr * 64 + fr, col0 = u.pn * BM + wc * 32 + 4 * fq;
;         f32x4 gv[2][2];
; #pragma unroll
;         for (int bj = 0; bj < 2; ++bj)
; #pragma unroll
;             for (int n = 0; n < 2; ++n) gv[bj][n] = *(const f32x4*)(gp + col0 + bj * HALF + n * 16);
; #pragma unroll
;         for (int ai = 0; ai < 2; ++ai)
; #pragma unroll
;             for (int m = 0; m < 4; ++m) { const size_t ro = (size_t)(row0 + ai * HALF + m * 16) * 1024 + col0;
; #pragma unroll
;                 for (int bj = 0; bj < 2; ++bj)
; #pragma unroll
;                     for (int n = 0; n < 2; ++n) { const f32x4 x = *(const f32x4*)(inb + ro + bj * HALF + n * 16);
;                         *(f32x4*)(outb + ro + bj * HALF + n * 16) = x + gv[bj][n] * acc[ai][bj][m][n]; } }
.LBB0_1199:
	s_and_b64 s[2:3], exec, s[16:17]
	s_cselect_b32 s3, s65, s43
	s_cselect_b32 s2, s64, s42
	s_lshl_b64 s[26:27], s[26:27], 2
	s_add_u32 s26, s50, s26
	s_addc_u32 s27, s51, s27
	s_lshl_b32 s5, s18, 8
	s_add_i32 s19, s5, 0xffff8000
	s_and_b64 s[16:17], exec, s[16:17]
	s_cselect_b32 s5, s19, s5
	v_add_u32_e32 v174, s5, v160
	v_lshl_or_b32 v130, s11, 8, v161
	v_ashrrev_i32_e32 v175, 31, v174
	v_ashrrev_i32_e32 v131, 31, v130
	v_lshlrev_b64 v[146:147], 12, v[174:175]
	v_lshlrev_b64 v[172:173], 2, v[130:131]
	v_lshl_add_u64 v[146:147], s[2:3], 0, v[146:147]
	v_lshl_add_u64 v[130:131], s[26:27], 0, v[172:173]
	v_lshl_add_u64 v[170:171], v[146:147], 0, v[172:173]
	global_load_dwordx4 v[142:145], v[130:131], off
	global_load_dwordx4 v[138:141], v[130:131], off offset:64
	global_load_dwordx4 v[134:137], v[130:131], off offset:512
	s_nop 0
	global_load_dwordx4 v[130:133], v[130:131], off offset:576
	s_nop 0
	s_mov_b64 s[98:99], 0x10000
	v_lshl_add_u64 v[176:177], v[170:171], 0, s[98:99]
	s_mov_b64 s[98:99], 0x20000
	v_lshl_add_u64 v[178:179], v[170:171], 0, s[98:99]
	s_mov_b64 s[98:99], 0x30000
	v_lshl_add_u64 v[180:181], v[170:171], 0, s[98:99]
	s_mov_b64 s[98:99], 0x80000
	v_lshl_add_u64 v[182:183], v[170:171], 0, s[98:99]
	s_mov_b64 s[98:99], 0x90000
	v_lshl_add_u64 v[184:185], v[170:171], 0, s[98:99]
	s_mov_b64 s[98:99], 0xa0000
	v_lshl_add_u64 v[186:187], v[170:171], 0, s[98:99]
	s_mov_b64 s[98:99], 0xb0000
	v_lshl_add_u64 v[188:189], v[170:171], 0, s[98:99]
	global_load_dwordx4 v[204:207], v[170:171], off
	global_load_dwordx4 v[212:215], v[170:171], off offset:64
	global_load_dwordx4 v[224:227], v[170:171], off offset:512
	global_load_dwordx4 v[228:231], v[170:171], off offset:576
	global_load_dwordx4 v[232:235], v[176:177], off
	global_load_dwordx4 v[236:239], v[176:177], off offset:64
	global_load_dwordx4 v[240:243], v[176:177], off offset:512
	global_load_dwordx4 v[244:247], v[176:177], off offset:576
	global_load_dwordx4 v[248:251], v[178:179], off
	global_load_dwordx4 v[218:221], v[178:179], off offset:64
	global_load_dwordx4 v[172:175], v[178:179], off offset:512
	global_load_dwordx4 v[150:153], v[178:179], off offset:576
	global_load_dwordx4 v[190:193], v[180:181], off
	global_load_dwordx4 v[194:197], v[180:181], off offset:64
	global_load_dwordx4 v[198:201], v[180:181], off offset:512
	s_waitcnt vmcnt(14)
	v_pk_fma_f32 v[206:207], v[128:129], v[144:145], v[206:207]
	v_pk_fma_f32 v[204:205], v[126:127], v[142:143], v[204:205]
	global_store_dwordx4 v[170:171], v[204:207], off
	global_load_dwordx4 v[126:129], v[180:181], off offset:576
	s_waitcnt vmcnt(15)
	v_pk_fma_f32 v[214:215], v[124:125], v[140:141], v[214:215]
	v_pk_fma_f32 v[212:213], v[122:123], v[138:139], v[212:213]
	global_store_dwordx4 v[170:171], v[212:215], off offset:64
	global_load_dwordx4 v[204:207], v[182:183], off
	global_load_dwordx4 v[122:125], v[182:183], off offset:64
	s_waitcnt vmcnt(17)
	v_pk_fma_f32 v[226:227], v[112:113], v[136:137], v[226:227]
	v_pk_fma_f32 v[224:225], v[110:111], v[134:135], v[224:225]
	global_store_dwordx4 v[170:171], v[224:227], off offset:512
	global_load_dwordx4 v[212:215], v[182:183], off offset:512
	global_load_dwordx4 v[110:113], v[182:183], off offset:576
	s_waitcnt vmcnt(19)
	v_pk_fma_f32 v[230:231], v[104:105], v[132:133], v[230:231]
	v_pk_fma_f32 v[228:229], v[102:103], v[130:131], v[228:229]
	global_store_dwordx4 v[170:171], v[228:231], off offset:576
	global_load_dwordx4 v[224:227], v[184:185], off
	global_load_dwordx4 v[102:105], v[184:185], off offset:64
	s_waitcnt vmcnt(21)
	v_pk_fma_f32 v[234:235], v[120:121], v[144:145], v[234:235]
	v_pk_fma_f32 v[232:233], v[118:119], v[142:143], v[232:233]
	global_store_dwordx4 v[176:177], v[232:235], off
	global_load_dwordx4 v[228:231], v[184:185], off offset:512
	global_load_dwordx4 v[118:121], v[184:185], off offset:576
	s_waitcnt vmcnt(23)
	v_pk_fma_f32 v[238:239], v[116:117], v[140:141], v[238:239]
	v_pk_fma_f32 v[236:237], v[114:115], v[138:139], v[236:237]
	global_store_dwordx4 v[176:177], v[236:239], off offset:64
	global_load_dwordx4 v[232:235], v[186:187], off
	global_load_dwordx4 v[114:117], v[186:187], off offset:64
	s_waitcnt vmcnt(25)
	v_pk_fma_f32 v[242:243], v[96:97], v[136:137], v[242:243]
	v_pk_fma_f32 v[240:241], v[94:95], v[134:135], v[240:241]
	global_store_dwordx4 v[176:177], v[240:243], off offset:512
	global_load_dwordx4 v[236:239], v[186:187], off offset:512
	global_load_dwordx4 v[94:97], v[186:187], off offset:576
	s_waitcnt vmcnt(27)
	v_pk_fma_f32 v[246:247], v[88:89], v[132:133], v[246:247]
	v_pk_fma_f32 v[244:245], v[86:87], v[130:131], v[244:245]
	global_store_dwordx4 v[176:177], v[244:247], off offset:576
	global_load_dwordx4 v[240:243], v[188:189], off
	global_load_dwordx4 v[86:89], v[188:189], off offset:64
	s_waitcnt vmcnt(29)
;     __device__ __forceinline__ void operator()(const f32x4 (&acc)[2][2][4][2], const Unit& u, int wr, int wc, int fr, int fq) const {
;     ...
;         for (int ai = 0; ai < 2; ++ai)
; #pragma unroll
;             for (int m = 0; m < 4; ++m) { const size_t ro = (size_t)(row0 + ai * HALF + m * 16) * 1024 + col0;
; #pragma unroll
;                 for (int bj = 0; bj < 2; ++bj)
; #pragma unroll
;                     for (int n = 0; n < 2; ++n) { const f32x4 x = *(const f32x4*)(inb + ro + bj * HALF + n * 16);
;                         *(f32x4*)(outb + ro + bj * HALF + n * 16) = x + gv[bj][n] * acc[ai][bj][m][n]; } }
	v_pk_fma_f32 v[250:251], v[108:109], v[144:145], v[250:251]
	v_pk_fma_f32 v[248:249], v[106:107], v[142:143], v[248:249]
	global_store_dwordx4 v[178:179], v[248:251], off
	global_load_dwordx4 v[244:247], v[188:189], off offset:512
	global_load_dwordx4 v[106:109], v[188:189], off offset:576
	s_waitcnt vmcnt(31)
	v_pk_fma_f32 v[220:221], v[100:101], v[140:141], v[220:221]
	v_pk_fma_f32 v[218:219], v[98:99], v[138:139], v[218:219]
	global_store_dwordx4 v[178:179], v[218:221], off offset:64
	s_waitcnt vmcnt(31)
	v_pk_fma_f32 v[174:175], v[80:81], v[136:137], v[174:175]
	v_pk_fma_f32 v[172:173], v[78:79], v[134:135], v[172:173]
	global_store_dwordx4 v[178:179], v[172:175], off offset:512
	s_waitcnt vmcnt(31)
	v_pk_fma_f32 v[152:153], v[76:77], v[132:133], v[152:153]
	v_pk_fma_f32 v[150:151], v[74:75], v[130:131], v[150:151]
	global_store_dwordx4 v[178:179], v[150:153], off offset:576
	s_waitcnt vmcnt(31)
	v_pk_fma_f32 v[192:193], v[92:93], v[144:145], v[192:193]
	v_pk_fma_f32 v[190:191], v[90:91], v[142:143], v[190:191]
	global_store_dwordx4 v[180:181], v[190:193], off
	s_waitcnt vmcnt(31)
	v_pk_fma_f32 v[196:197], v[84:85], v[140:141], v[196:197]
	v_pk_fma_f32 v[194:195], v[82:83], v[138:139], v[194:195]
	global_store_dwordx4 v[180:181], v[194:197], off offset:64
	s_waitcnt vmcnt(31)
	v_pk_fma_f32 v[200:201], v[72:73], v[136:137], v[200:201]
	v_pk_fma_f32 v[198:199], v[70:71], v[134:135], v[198:199]
	global_store_dwordx4 v[180:181], v[198:201], off offset:512
	s_waitcnt vmcnt(30)
	v_pk_fma_f32 v[128:129], v[68:69], v[132:133], v[128:129]
	v_pk_fma_f32 v[126:127], v[66:67], v[130:131], v[126:127]
	global_store_dwordx4 v[180:181], v[126:129], off offset:576
	s_waitcnt vmcnt(29)
	v_pk_fma_f32 v[206:207], v[64:65], v[144:145], v[206:207]
	v_pk_fma_f32 v[204:205], v[62:63], v[142:143], v[204:205]
	global_store_dwordx4 v[182:183], v[204:207], off
	s_waitcnt vmcnt(29)
	v_pk_fma_f32 v[124:125], v[60:61], v[140:141], v[124:125]
	v_pk_fma_f32 v[122:123], v[58:59], v[138:139], v[122:123]
	global_store_dwordx4 v[182:183], v[122:125], off offset:64
	s_waitcnt vmcnt(28)
	v_pk_fma_f32 v[214:215], v[48:49], v[136:137], v[214:215]
	v_pk_fma_f32 v[212:213], v[46:47], v[134:135], v[212:213]
	global_store_dwordx4 v[182:183], v[212:215], off offset:512
	s_waitcnt vmcnt(28)
	v_pk_fma_f32 v[112:113], v[44:45], v[132:133], v[112:113]
	v_pk_fma_f32 v[110:111], v[42:43], v[130:131], v[110:111]
	global_store_dwordx4 v[182:183], v[110:113], off offset:576
	s_waitcnt vmcnt(27)
	v_pk_fma_f32 v[226:227], v[56:57], v[144:145], v[226:227]
	v_pk_fma_f32 v[224:225], v[54:55], v[142:143], v[224:225]
	global_store_dwordx4 v[184:185], v[224:227], off
	s_waitcnt vmcnt(27)
	v_pk_fma_f32 v[104:105], v[52:53], v[140:141], v[104:105]
	v_pk_fma_f32 v[102:103], v[50:51], v[138:139], v[102:103]
	global_store_dwordx4 v[184:185], v[102:105], off offset:64
	s_waitcnt vmcnt(26)
	v_pk_fma_f32 v[230:231], v[32:33], v[136:137], v[230:231]
	v_pk_fma_f32 v[228:229], v[30:31], v[134:135], v[228:229]
	global_store_dwordx4 v[184:185], v[228:231], off offset:512
	s_waitcnt vmcnt(26)
	v_pk_fma_f32 v[120:121], v[28:29], v[132:133], v[120:121]
	v_pk_fma_f32 v[118:119], v[26:27], v[130:131], v[118:119]
	global_store_dwordx4 v[184:185], v[118:121], off offset:576
	s_waitcnt vmcnt(25)
	v_pk_fma_f32 v[234:235], v[40:41], v[144:145], v[234:235]
	v_pk_fma_f32 v[232:233], v[38:39], v[142:143], v[232:233]
	global_store_dwordx4 v[186:187], v[232:235], off
	s_waitcnt vmcnt(25)
	v_pk_fma_f32 v[116:117], v[36:37], v[140:141], v[116:117]
	v_pk_fma_f32 v[114:115], v[34:35], v[138:139], v[114:115]
	global_store_dwordx4 v[186:187], v[114:117], off offset:64
	s_waitcnt vmcnt(24)
	v_pk_fma_f32 v[238:239], v[16:17], v[136:137], v[238:239]
	v_pk_fma_f32 v[236:237], v[14:15], v[134:135], v[236:237]
	global_store_dwordx4 v[186:187], v[236:239], off offset:512
	s_waitcnt vmcnt(24)
	v_pk_fma_f32 v[96:97], v[12:13], v[132:133], v[96:97]
	v_pk_fma_f32 v[94:95], v[10:11], v[130:131], v[94:95]
	global_store_dwordx4 v[186:187], v[94:97], off offset:576
	s_waitcnt vmcnt(23)
	v_pk_fma_f32 v[242:243], v[24:25], v[144:145], v[242:243]
	v_pk_fma_f32 v[240:241], v[22:23], v[142:143], v[240:241]
	global_store_dwordx4 v[188:189], v[240:243], off
	s_waitcnt vmcnt(23)
	v_pk_fma_f32 v[88:89], v[20:21], v[140:141], v[88:89]
	v_pk_fma_f32 v[86:87], v[18:19], v[138:139], v[86:87]
	global_store_dwordx4 v[188:189], v[86:89], off offset:64
	s_waitcnt vmcnt(22)
	v_pk_fma_f32 v[246:247], v[8:9], v[136:137], v[246:247]
	v_pk_fma_f32 v[244:245], v[6:7], v[134:135], v[244:245]
	global_store_dwordx4 v[188:189], v[244:247], off offset:512
	s_waitcnt vmcnt(22)
	v_pk_fma_f32 v[108:109], v[4:5], v[132:133], v[108:109]
	v_pk_fma_f32 v[106:107], v[2:3], v[130:131], v[106:107]
	global_store_dwordx4 v[188:189], v[106:109], off offset:576
	s_mov_b64 s[2:3], 0
